# v43 plus: the scalar address / m0 preparation that opens each load segment of the GEMM K-loops is hoisted in front of the preceding barrier (behind the wave's last MFMA)
# baseline (speedup 1.0000x reference)
; #define PG8_STAGE(bufoff, gbase, voff) do { _Pragma("unroll") for (int _i = 0; _i < 2; ++_i) \
;         __builtin_amdgcn_global_load_lds((const unsigned*)((const char*)(gbase) + (voff)[_i]), (PG8_LAS unsigned*)(lds + (bufoff) + ldsw + _i * 8192), 16, 0, 0); } while (0)
; #define PG8_LDA(dst, b, h) do { _Pragma("unroll") for (int m = 0; m < 4; ++m) _Pragma("unroll") for (int k = 0; k < 2; ++k) dst[m][k] = *(const PG8_LAS bf16x8*)(lds + PG8_SA(b, h) + aoff + m * 2048 + k * 1024); } while (0)
; #define PG8_LDB(dst, b, h) do { _Pragma("unroll") for (int n = 0; n < 2; ++n) _Pragma("unroll") for (int k = 0; k < 2; ++k) dst[n][k] = *(const PG8_LAS bf16x8*)(lds + PG8_SB(b, h) + boff + n * 2048 + k * 1024); } while (0)
; #define PG8_MMA(ai, bj, At, Bt) do { __builtin_amdgcn_s_setprio(1); _Pragma("unroll") for (int m = 0; m < 4; ++m) _Pragma("unroll") for (int n = 0; n < 2; ++n) _Pragma("unroll") for (int k = 0; k < 2; ++k) \
;         acc[ai][bj][m][n] = __builtin_amdgcn_mfma_f32_16x16x32_bf16(Bt[n][k], At[m][k], acc[ai][bj][m][n], 0, 0, 0); __builtin_amdgcn_s_setprio(0); } while (0)
; #define PG8_BAR __builtin_amdgcn_s_barrier()
; template <class Epi, class Sched, bool ALIGN_EPI = false, bool SP2 = false>
; __device__ __forceinline__ void gemm_phase(PG8_LAS unsigned char* lds, const Gemm g, const Sched& S, const Epi& E) {
;     ...
;             const bool last = (t == nt - 2);
;             const char* a1 = cA + (size_t)(t + 1) * kstep;
;             const char* a2 = last ? nA : cA + (size_t)(t + 2) * kstep; const char* b2 = last ? nB : cB + (size_t)(t + 2) * kstep;
;             const char* a3 = a2 + kstep; const char* b3 = b2 + kstep;
;             if (last && has_next) S.a_ready(nxt);
;             if constexpr (SP2) {
;             PG8_LDB(B0, 0, 0); PG8_LDB(B1, 0, 1); PG8_SCHED; PG8_LDA(At, 0, 0); PG8_STAGE(PG8_SA(1, 1), a1 + hstep, voffA);
;             PG8_WAIT_V(8); PG8_WAIT_L(0); PG8_BAR; PG8_MMA(0, 0, At, B0); PG8_MMA(0, 1, At, B1); PG8_BAR; PG8_SCHED;
;             PG8_LDA(At, 0, 1); PG8_STAGE(PG8_SB(0, 0), b2, voffB); PG8_STAGE(PG8_SB(0, 1), b2 + hstepB, voffB); PG8_STAGE(PG8_SA(0, 0), a2, voffA);
;             PG8_WAIT_V(8); PG8_WAIT_L(0); PG8_BAR; PG8_MMA(1, 0, At, B0); PG8_MMA(1, 1, At, B1); PG8_BAR; PG8_SCHED;
;             PG8_LDB(B0, 1, 0); PG8_LDB(B1, 1, 1); PG8_SCHED; PG8_LDA(At, 1, 0); PG8_STAGE(PG8_SA(0, 1), a2 + hstep, voffA);
.LBB0_170:
	s_add_u32 s9, s70, s46
	s_addc_u32 s10, s71, s47
	s_add_u32 s9, s9, 0x100
	s_addc_u32 s10, s10, 0
	s_add_u32 s100, s9, 0x7ff80
	s_addc_u32 s101, s10, 0
	s_add_u32 s11, s93, s46
	s_addc_u32 s12, s94, s47
	s_add_i32 s13, 0, 0x10000
	s_cmpk_eq_i32 s46, 0xf00
	s_cselect_b32 s85, s4, s10
	s_cselect_b32 s84, s5, s9
	s_cselect_b32 s81, s6, s12
	s_cselect_b32 s80, s7, s11
	s_add_i32 s9, 0, 0x14000
	v_add_u32_e32 v160, s13, v139
	v_add_u32_e32 v178, s9, v139
	ds_read_b128 v[148:151], v160
	ds_read_b128 v[152:155], v160 offset:1024
	ds_read_b128 v[156:159], v160 offset:2048
	ds_read_b128 v[160:163], v160 offset:3072
	ds_read_b128 v[166:169], v178
	ds_read_b128 v[170:173], v178 offset:1024
	ds_read_b128 v[174:177], v178 offset:2048
	ds_read_b128 v[178:181], v178 offset:3072
	s_add_i32 m0, s1, 0xc000
	ds_read_b128 v[182:185], v165
	ds_read_b128 v[206:209], v165 offset:1024
	ds_read_b128 v[210:213], v165 offset:2048
	ds_read_b128 v[214:217], v165 offset:3072
	ds_read_b128 v[218:221], v165 offset:4096
	ds_read_b128 v[236:239], v165 offset:5120
	ds_read_b128 v[240:243], v165 offset:6144
	ds_read_b128 v[244:247], v165 offset:7168
	global_load_lds_dwordx4 v140, s[100:101]
	s_add_i32 m0, s1, 0xe000
	s_nop 0
	global_load_lds_dwordx4 v142, s[100:101]
	s_waitcnt vmcnt(8)
	s_waitcnt lgkmcnt(0)
	s_barrier
	v_mfma_f32_16x16x32_bf16 v[126:129], v[148:151], v[182:185], v[126:129]
	v_mfma_f32_16x16x32_bf16 v[122:125], v[156:159], v[182:185], v[122:125]
	v_mfma_f32_16x16x32_bf16 v[118:121], v[148:151], v[210:213], v[118:121]
	v_mfma_f32_16x16x32_bf16 v[114:117], v[156:159], v[210:213], v[114:117]
	v_mfma_f32_16x16x32_bf16 v[110:113], v[148:151], v[218:221], v[110:113]
	v_mfma_f32_16x16x32_bf16 v[106:109], v[156:159], v[218:221], v[106:109]
	v_mfma_f32_16x16x32_bf16 v[102:105], v[148:151], v[240:243], v[102:105]
	v_mfma_f32_16x16x32_bf16 v[98:101], v[156:159], v[240:243], v[98:101]
	v_mfma_f32_16x16x32_bf16 v[126:129], v[152:155], v[206:209], v[126:129]
	v_mfma_f32_16x16x32_bf16 v[122:125], v[160:163], v[206:209], v[122:125]
	v_mfma_f32_16x16x32_bf16 v[118:121], v[152:155], v[214:217], v[118:121]
	v_mfma_f32_16x16x32_bf16 v[114:117], v[160:163], v[214:217], v[114:117]
	v_mfma_f32_16x16x32_bf16 v[110:113], v[152:155], v[236:239], v[110:113]
	v_mfma_f32_16x16x32_bf16 v[106:109], v[160:163], v[236:239], v[106:109]
	v_mfma_f32_16x16x32_bf16 v[102:105], v[152:155], v[244:247], v[102:105]
	v_mfma_f32_16x16x32_bf16 v[98:101], v[160:163], v[244:247], v[98:101]
	v_mfma_f32_16x16x32_bf16 v[94:97], v[166:169], v[182:185], v[94:97]
	v_mfma_f32_16x16x32_bf16 v[90:93], v[174:177], v[182:185], v[90:93]
	v_mfma_f32_16x16x32_bf16 v[86:89], v[166:169], v[210:213], v[86:89]
	v_mfma_f32_16x16x32_bf16 v[82:85], v[174:177], v[210:213], v[82:85]
	v_mfma_f32_16x16x32_bf16 v[78:81], v[166:169], v[218:221], v[78:81]
	v_mfma_f32_16x16x32_bf16 v[74:77], v[174:177], v[218:221], v[74:77]
	v_mfma_f32_16x16x32_bf16 v[70:73], v[166:169], v[240:243], v[70:73]
	v_mfma_f32_16x16x32_bf16 v[66:69], v[174:177], v[240:243], v[66:69]
	v_mfma_f32_16x16x32_bf16 v[94:97], v[170:173], v[206:209], v[94:97]
	v_mfma_f32_16x16x32_bf16 v[90:93], v[178:181], v[206:209], v[90:93]
	v_mfma_f32_16x16x32_bf16 v[86:89], v[170:173], v[214:217], v[86:89]
	v_mfma_f32_16x16x32_bf16 v[82:85], v[178:181], v[214:217], v[82:85]
	v_mfma_f32_16x16x32_bf16 v[78:81], v[170:173], v[236:239], v[78:81]
	v_mfma_f32_16x16x32_bf16 v[74:77], v[178:181], v[236:239], v[74:77]
	v_mfma_f32_16x16x32_bf16 v[70:73], v[170:173], v[244:247], v[70:73]
	v_mfma_f32_16x16x32_bf16 v[66:69], v[178:181], v[244:247], v[66:69]
	s_add_i32 s10, s13, s0
	s_mov_b32 m0, s10
	s_barrier
	ds_read_b128 v[182:185], v165 offset:16384
	ds_read_b128 v[206:209], v165 offset:17408
	ds_read_b128 v[210:213], v165 offset:18432
	ds_read_b128 v[214:217], v165 offset:19456
	ds_read_b128 v[218:221], v165 offset:20480
	ds_read_b128 v[236:239], v165 offset:21504
	ds_read_b128 v[240:243], v165 offset:22528
	ds_read_b128 v[244:247], v165 offset:23552
	global_load_lds_dwordx4 v132, s[80:81]
	s_add_i32 m0, s10, 0x2000
	s_add_u32 s10, s80, 0x20000
	s_addc_u32 s11, s81, 0
	s_add_i32 s9, s9, s0
	global_load_lds_dwordx4 v136, s[80:81]
	s_mov_b32 m0, s9
	s_nop 0
	global_load_lds_dwordx4 v132, s[10:11]
	s_add_i32 m0, s9, 0x2000
	s_nop 0
	global_load_lds_dwordx4 v136, s[10:11]
	s_mov_b32 m0, s1
	s_nop 0
	global_load_lds_dwordx4 v130, s[84:85]
	s_mov_b32 m0, s25
	s_nop 0
	global_load_lds_dwordx4 v134, s[84:85]
	s_waitcnt vmcnt(8)
	s_waitcnt lgkmcnt(0)
	s_barrier
	v_mfma_f32_16x16x32_bf16 v[62:65], v[148:151], v[182:185], v[62:65]
	v_mfma_f32_16x16x32_bf16 v[58:61], v[156:159], v[182:185], v[58:61]
	v_mfma_f32_16x16x32_bf16 v[54:57], v[148:151], v[210:213], v[54:57]
	v_mfma_f32_16x16x32_bf16 v[50:53], v[156:159], v[210:213], v[50:53]
	v_mfma_f32_16x16x32_bf16 v[46:49], v[148:151], v[218:221], v[46:49]
	v_mfma_f32_16x16x32_bf16 v[42:45], v[156:159], v[218:221], v[42:45]
	v_mfma_f32_16x16x32_bf16 v[38:41], v[148:151], v[240:243], v[38:41]
	v_mfma_f32_16x16x32_bf16 v[34:37], v[156:159], v[240:243], v[34:37]
	v_mfma_f32_16x16x32_bf16 v[62:65], v[152:155], v[206:209], v[62:65]
	v_mfma_f32_16x16x32_bf16 v[58:61], v[160:163], v[206:209], v[58:61]
	v_mfma_f32_16x16x32_bf16 v[54:57], v[152:155], v[214:217], v[54:57]
	v_mfma_f32_16x16x32_bf16 v[50:53], v[160:163], v[214:217], v[50:53]
	v_mfma_f32_16x16x32_bf16 v[46:49], v[152:155], v[236:239], v[46:49]
	v_mfma_f32_16x16x32_bf16 v[42:45], v[160:163], v[236:239], v[42:45]
	v_mfma_f32_16x16x32_bf16 v[38:41], v[152:155], v[244:247], v[38:41]
	v_mfma_f32_16x16x32_bf16 v[34:37], v[160:163], v[244:247], v[34:37]
	v_mfma_f32_16x16x32_bf16 v[30:33], v[166:169], v[182:185], v[30:33]
	v_mfma_f32_16x16x32_bf16 v[26:29], v[174:177], v[182:185], v[26:29]
	v_mfma_f32_16x16x32_bf16 v[22:25], v[166:169], v[210:213], v[22:25]
	v_mfma_f32_16x16x32_bf16 v[18:21], v[174:177], v[210:213], v[18:21]
	v_mfma_f32_16x16x32_bf16 v[14:17], v[166:169], v[218:221], v[14:17]
	v_mfma_f32_16x16x32_bf16 v[10:13], v[174:177], v[218:221], v[10:13]
	v_mfma_f32_16x16x32_bf16 v[6:9], v[166:169], v[240:243], v[6:9]
	v_mfma_f32_16x16x32_bf16 v[2:5], v[174:177], v[240:243], v[2:5]
	v_mfma_f32_16x16x32_bf16 v[30:33], v[170:173], v[206:209], v[30:33]
	v_mfma_f32_16x16x32_bf16 v[26:29], v[178:181], v[206:209], v[26:29]
	v_mfma_f32_16x16x32_bf16 v[22:25], v[170:173], v[214:217], v[22:25]
	v_mfma_f32_16x16x32_bf16 v[18:21], v[178:181], v[214:217], v[18:21]
	v_mfma_f32_16x16x32_bf16 v[14:17], v[170:173], v[236:239], v[14:17]
	v_mfma_f32_16x16x32_bf16 v[10:13], v[178:181], v[236:239], v[10:13]
	v_mfma_f32_16x16x32_bf16 v[6:9], v[170:173], v[244:247], v[6:9]
	v_mfma_f32_16x16x32_bf16 v[2:5], v[178:181], v[244:247], v[2:5]
	s_add_i32 s9, 0, 0x18000
	s_add_i32 s12, 0, 0x1c000
	s_barrier
; #define PG8_STAGE(bufoff, gbase, voff) do { _Pragma("unroll") for (int _i = 0; _i < 2; ++_i) \
;         __builtin_amdgcn_global_load_lds((const unsigned*)((const char*)(gbase) + (voff)[_i]), (PG8_LAS unsigned*)(lds + (bufoff) + ldsw + _i * 8192), 16, 0, 0); } while (0)
; #define PG8_LDA(dst, b, h) do { _Pragma("unroll") for (int m = 0; m < 4; ++m) _Pragma("unroll") for (int k = 0; k < 2; ++k) dst[m][k] = *(const PG8_LAS bf16x8*)(lds + PG8_SA(b, h) + aoff + m * 2048 + k * 1024); } while (0)
; #define PG8_LDB(dst, b, h) do { _Pragma("unroll") for (int n = 0; n < 2; ++n) _Pragma("unroll") for (int k = 0; k < 2; ++k) dst[n][k] = *(const PG8_LAS bf16x8*)(lds + PG8_SB(b, h) + boff + n * 2048 + k * 1024); } while (0)
; #define PG8_MMA(ai, bj, At, Bt) do { __builtin_amdgcn_s_setprio(1); _Pragma("unroll") for (int m = 0; m < 4; ++m) _Pragma("unroll") for (int n = 0; n < 2; ++n) _Pragma("unroll") for (int k = 0; k < 2; ++k) \
;         acc[ai][bj][m][n] = __builtin_amdgcn_mfma_f32_16x16x32_bf16(Bt[n][k], At[m][k], acc[ai][bj][m][n], 0, 0, 0); __builtin_amdgcn_s_setprio(0); } while (0)
; #define PG8_WAIT_V(n) asm volatile("s_waitcnt vmcnt(" #n ")" ::: "memory")
; #define PG8_WAIT_L(n) asm volatile("s_waitcnt lgkmcnt(" #n ")" ::: "memory")
; #define PG8_BAR __builtin_amdgcn_s_barrier()
; #define PG8_SCHED __builtin_amdgcn_sched_barrier(0)
; template <class Epi, class Sched, bool ALIGN_EPI = false, bool SP2 = false>
; __device__ __forceinline__ void gemm_phase(PG8_LAS unsigned char* lds, const Gemm g, const Sched& S, const Epi& E) {
;     ...
;             PG8_LDB(B0, 1, 0); PG8_LDB(B1, 1, 1); PG8_SCHED; PG8_LDA(At, 1, 0); PG8_STAGE(PG8_SA(0, 1), a2 + hstep, voffA);
;             PG8_WAIT_V(8); PG8_WAIT_L(0); PG8_BAR; PG8_MMA(0, 0, At, B0); PG8_MMA(0, 1, At, B1); PG8_BAR; PG8_SCHED;
;             PG8_LDA(At, 1, 1); PG8_STAGE(PG8_SB(1, 0), b3, voffB); PG8_STAGE(PG8_SB(1, 1), b3 + hstepB, voffB); PG8_STAGE(PG8_SA(1, 0), a3, voffA);
;             PG8_WAIT_V(8); PG8_WAIT_L(0); PG8_BAR; PG8_MMA(1, 0, At, B0); PG8_MMA(1, 1, At, B1); PG8_BAR; PG8_SCHED;
	v_add_u32_e32 v160, s9, v139
	v_add_u32_e32 v178, s12, v139
	ds_read_b128 v[148:151], v160
	ds_read_b128 v[152:155], v160 offset:1024
	ds_read_b128 v[156:159], v160 offset:2048
	ds_read_b128 v[160:163], v160 offset:3072
	ds_read_b128 v[166:169], v178
	ds_read_b128 v[170:173], v178 offset:1024
	ds_read_b128 v[174:177], v178 offset:2048
	ds_read_b128 v[178:181], v178 offset:3072
	s_add_u32 s10, s84, 0x80000
	s_addc_u32 s11, s85, 0
	s_mov_b32 m0, s42
	ds_read_b128 v[182:185], v165 offset:32768
	ds_read_b128 v[206:209], v165 offset:33792
	ds_read_b128 v[210:213], v165 offset:34816
	ds_read_b128 v[214:217], v165 offset:35840
	ds_read_b128 v[218:221], v165 offset:36864
	ds_read_b128 v[236:239], v165 offset:37888
	ds_read_b128 v[240:243], v165 offset:38912
	ds_read_b128 v[244:247], v165 offset:39936
	global_load_lds_dwordx4 v130, s[10:11]
	s_mov_b32 m0, s51
	s_nop 0
	global_load_lds_dwordx4 v134, s[10:11]
	s_waitcnt vmcnt(8)
	s_waitcnt lgkmcnt(0)
	s_barrier
	v_mfma_f32_16x16x32_bf16 v[126:129], v[148:151], v[182:185], v[126:129]
	v_mfma_f32_16x16x32_bf16 v[122:125], v[156:159], v[182:185], v[122:125]
	v_mfma_f32_16x16x32_bf16 v[118:121], v[148:151], v[210:213], v[118:121]
	v_mfma_f32_16x16x32_bf16 v[114:117], v[156:159], v[210:213], v[114:117]
	v_mfma_f32_16x16x32_bf16 v[110:113], v[148:151], v[218:221], v[110:113]
	v_mfma_f32_16x16x32_bf16 v[106:109], v[156:159], v[218:221], v[106:109]
	v_mfma_f32_16x16x32_bf16 v[102:105], v[148:151], v[240:243], v[102:105]
	v_mfma_f32_16x16x32_bf16 v[98:101], v[156:159], v[240:243], v[98:101]
	v_mfma_f32_16x16x32_bf16 v[126:129], v[152:155], v[206:209], v[126:129]
	v_mfma_f32_16x16x32_bf16 v[122:125], v[160:163], v[206:209], v[122:125]
	v_mfma_f32_16x16x32_bf16 v[118:121], v[152:155], v[214:217], v[118:121]
	v_mfma_f32_16x16x32_bf16 v[114:117], v[160:163], v[214:217], v[114:117]
	v_mfma_f32_16x16x32_bf16 v[110:113], v[152:155], v[236:239], v[110:113]
	v_mfma_f32_16x16x32_bf16 v[106:109], v[160:163], v[236:239], v[106:109]
	v_mfma_f32_16x16x32_bf16 v[102:105], v[152:155], v[244:247], v[102:105]
	v_mfma_f32_16x16x32_bf16 v[98:101], v[160:163], v[244:247], v[98:101]
	v_mfma_f32_16x16x32_bf16 v[94:97], v[166:169], v[182:185], v[94:97]
	v_mfma_f32_16x16x32_bf16 v[90:93], v[174:177], v[182:185], v[90:93]
	v_mfma_f32_16x16x32_bf16 v[86:89], v[166:169], v[210:213], v[86:89]
	v_mfma_f32_16x16x32_bf16 v[82:85], v[174:177], v[210:213], v[82:85]
	v_mfma_f32_16x16x32_bf16 v[78:81], v[166:169], v[218:221], v[78:81]
	v_mfma_f32_16x16x32_bf16 v[74:77], v[174:177], v[218:221], v[74:77]
	v_mfma_f32_16x16x32_bf16 v[70:73], v[166:169], v[240:243], v[70:73]
	v_mfma_f32_16x16x32_bf16 v[66:69], v[174:177], v[240:243], v[66:69]
	v_mfma_f32_16x16x32_bf16 v[94:97], v[170:173], v[206:209], v[94:97]
	v_mfma_f32_16x16x32_bf16 v[90:93], v[178:181], v[206:209], v[90:93]
	v_mfma_f32_16x16x32_bf16 v[86:89], v[170:173], v[214:217], v[86:89]
	v_mfma_f32_16x16x32_bf16 v[82:85], v[178:181], v[214:217], v[82:85]
	v_mfma_f32_16x16x32_bf16 v[78:81], v[170:173], v[236:239], v[78:81]
	v_mfma_f32_16x16x32_bf16 v[74:77], v[178:181], v[236:239], v[74:77]
	v_mfma_f32_16x16x32_bf16 v[70:73], v[170:173], v[244:247], v[70:73]
	v_mfma_f32_16x16x32_bf16 v[66:69], v[178:181], v[244:247], v[66:69]
	s_add_i32 s9, s9, s0
	s_mov_b32 m0, s9
	s_barrier
	ds_read_b128 v[182:185], v165 offset:49152
	ds_read_b128 v[206:209], v165 offset:50176
	ds_read_b128 v[210:213], v165 offset:51200
	ds_read_b128 v[214:217], v165 offset:52224
	ds_read_b128 v[218:221], v165 offset:53248
	ds_read_b128 v[236:239], v165 offset:54272
	ds_read_b128 v[240:243], v165 offset:55296
	ds_read_b128 v[244:247], v165 offset:56320
	s_add_u32 s100, s80, s60
	s_addc_u32 s101, s81, s61
	global_load_lds_dwordx4 v132, s[100:101]
	s_add_i32 m0, s9, 0x2000
	s_add_u32 s10, s80, 0x20080
	s_addc_u32 s11, s81, 0
	s_add_i32 s9, s12, s0
	global_load_lds_dwordx4 v136, s[100:101]
	s_mov_b32 m0, s9
	s_nop 0
	global_load_lds_dwordx4 v132, s[10:11]
	s_add_i32 m0, s9, 0x2000
	s_nop 0
	global_load_lds_dwordx4 v136, s[10:11]
	s_mov_b32 m0, s66
	s_add_u32 s100, s84, s60
	s_addc_u32 s101, s85, s61
	global_load_lds_dwordx4 v130, s[100:101]
	s_mov_b32 m0, s67
	s_nop 0
	global_load_lds_dwordx4 v134, s[100:101]
	s_waitcnt vmcnt(8)
	s_waitcnt lgkmcnt(0)
	s_barrier
	v_mfma_f32_16x16x32_bf16 v[62:65], v[148:151], v[182:185], v[62:65]
	v_mfma_f32_16x16x32_bf16 v[58:61], v[156:159], v[182:185], v[58:61]
	v_mfma_f32_16x16x32_bf16 v[54:57], v[148:151], v[210:213], v[54:57]
	v_mfma_f32_16x16x32_bf16 v[50:53], v[156:159], v[210:213], v[50:53]
	v_mfma_f32_16x16x32_bf16 v[46:49], v[148:151], v[218:221], v[46:49]
	v_mfma_f32_16x16x32_bf16 v[42:45], v[156:159], v[218:221], v[42:45]
	v_mfma_f32_16x16x32_bf16 v[38:41], v[148:151], v[240:243], v[38:41]
	v_mfma_f32_16x16x32_bf16 v[34:37], v[156:159], v[240:243], v[34:37]
	v_mfma_f32_16x16x32_bf16 v[62:65], v[152:155], v[206:209], v[62:65]
	v_mfma_f32_16x16x32_bf16 v[58:61], v[160:163], v[206:209], v[58:61]
	v_mfma_f32_16x16x32_bf16 v[54:57], v[152:155], v[214:217], v[54:57]
	v_mfma_f32_16x16x32_bf16 v[50:53], v[160:163], v[214:217], v[50:53]
	v_mfma_f32_16x16x32_bf16 v[46:49], v[152:155], v[236:239], v[46:49]
	v_mfma_f32_16x16x32_bf16 v[42:45], v[160:163], v[236:239], v[42:45]
	v_mfma_f32_16x16x32_bf16 v[38:41], v[152:155], v[244:247], v[38:41]
	v_mfma_f32_16x16x32_bf16 v[34:37], v[160:163], v[244:247], v[34:37]
	v_mfma_f32_16x16x32_bf16 v[30:33], v[166:169], v[182:185], v[30:33]
	v_mfma_f32_16x16x32_bf16 v[26:29], v[174:177], v[182:185], v[26:29]
	v_mfma_f32_16x16x32_bf16 v[22:25], v[166:169], v[210:213], v[22:25]
	v_mfma_f32_16x16x32_bf16 v[18:21], v[174:177], v[210:213], v[18:21]
	v_mfma_f32_16x16x32_bf16 v[14:17], v[166:169], v[218:221], v[14:17]
	v_mfma_f32_16x16x32_bf16 v[10:13], v[174:177], v[218:221], v[10:13]
	v_mfma_f32_16x16x32_bf16 v[6:9], v[166:169], v[240:243], v[6:9]
	v_mfma_f32_16x16x32_bf16 v[2:5], v[174:177], v[240:243], v[2:5]
	v_mfma_f32_16x16x32_bf16 v[30:33], v[170:173], v[206:209], v[30:33]
	v_mfma_f32_16x16x32_bf16 v[26:29], v[178:181], v[206:209], v[26:29]
	v_mfma_f32_16x16x32_bf16 v[22:25], v[170:173], v[214:217], v[22:25]
	v_mfma_f32_16x16x32_bf16 v[18:21], v[178:181], v[214:217], v[18:21]
	v_mfma_f32_16x16x32_bf16 v[14:17], v[170:173], v[236:239], v[14:17]
	v_mfma_f32_16x16x32_bf16 v[10:13], v[178:181], v[236:239], v[10:13]
	v_mfma_f32_16x16x32_bf16 v[6:9], v[170:173], v[244:247], v[6:9]
	v_mfma_f32_16x16x32_bf16 v[2:5], v[178:181], v[244:247], v[2:5]
	s_add_i32 s8, s8, 2
	s_add_u32 s46, s46, 0x100
	s_addc_u32 s47, s47, 0
	s_cmp_gt_u32 s8, 29
	s_barrier
	s_cbranch_scc0 .LBB0_170
	s_and_b64 vcc, exec, s[54:55]
	s_cbranch_vccz .LBB0_173
	s_barrier

; #define PG8_STAGE(bufoff, gbase, voff) do { _Pragma("unroll") for (int _i = 0; _i < 2; ++_i) \
;         __builtin_amdgcn_global_load_lds((const unsigned*)((const char*)(gbase) + (voff)[_i]), (PG8_LAS unsigned*)(lds + (bufoff) + ldsw + _i * 8192), 16, 0, 0); } while (0)
; #define PG8_LDA(dst, b, h) do { _Pragma("unroll") for (int m = 0; m < 4; ++m) _Pragma("unroll") for (int k = 0; k < 2; ++k) dst[m][k] = *(const PG8_LAS bf16x8*)(lds + PG8_SA(b, h) + aoff + m * 2048 + k * 1024); } while (0)
; #define PG8_LDB(dst, b, h) do { _Pragma("unroll") for (int n = 0; n < 2; ++n) _Pragma("unroll") for (int k = 0; k < 2; ++k) dst[n][k] = *(const PG8_LAS bf16x8*)(lds + PG8_SB(b, h) + boff + n * 2048 + k * 1024); } while (0)
; #define PG8_MMA(ai, bj, At, Bt) do { __builtin_amdgcn_s_setprio(1); _Pragma("unroll") for (int m = 0; m < 4; ++m) _Pragma("unroll") for (int n = 0; n < 2; ++n) _Pragma("unroll") for (int k = 0; k < 2; ++k) \
;         acc[ai][bj][m][n] = __builtin_amdgcn_mfma_f32_16x16x32_bf16(Bt[n][k], At[m][k], acc[ai][bj][m][n], 0, 0, 0); __builtin_amdgcn_s_setprio(0); } while (0)
; #define PG8_BAR __builtin_amdgcn_s_barrier()
; template <class Epi, class Sched, bool ALIGN_EPI = false, bool SP2 = false>
; __device__ __forceinline__ void gemm_phase(PG8_LAS unsigned char* lds, const Gemm g, const Sched& S, const Epi& E) {
;     ...
;             const bool last = (t == nt - 2);
;             const char* a1 = cA + (size_t)(t + 1) * kstep;
;             const char* a2 = last ? nA : cA + (size_t)(t + 2) * kstep; const char* b2 = last ? nB : cB + (size_t)(t + 2) * kstep;
;             const char* a3 = a2 + kstep; const char* b3 = b2 + kstep;
;             if (last && has_next) S.a_ready(nxt);
;             if constexpr (SP2) {
;             PG8_LDB(B0, 0, 0); PG8_LDB(B1, 0, 1); PG8_SCHED; PG8_LDA(At, 0, 0); PG8_STAGE(PG8_SA(1, 1), a1 + hstep, voffA);
;             PG8_WAIT_V(8); PG8_WAIT_L(0); PG8_BAR; PG8_MMA(0, 0, At, B0); PG8_MMA(0, 1, At, B1); PG8_BAR; PG8_SCHED;
;             PG8_LDA(At, 0, 1); PG8_STAGE(PG8_SB(0, 0), b2, voffB); PG8_STAGE(PG8_SB(0, 1), b2 + hstepB, voffB); PG8_STAGE(PG8_SA(0, 0), a2, voffA);
;             PG8_WAIT_V(8); PG8_WAIT_L(0); PG8_BAR; PG8_MMA(1, 0, At, B0); PG8_MMA(1, 1, At, B1); PG8_BAR; PG8_SCHED;
;             PG8_LDB(B0, 1, 0); PG8_LDB(B1, 1, 1); PG8_SCHED; PG8_LDA(At, 1, 0); PG8_STAGE(PG8_SA(0, 1), a2 + hstep, voffA);
.LBB0_788:
	s_add_u32 s9, s68, 0xfffe0080
	s_addc_u32 s10, s69, -1
	s_add_i32 s11, 0, 0x10000
	s_cmp_eq_u32 s8, 4
	s_cselect_b32 s77, s36, s10
	s_cselect_b32 s76, s37, s9
	s_cselect_b32 s73, s4, s7
	s_cselect_b32 s72, s5, s6
	s_add_i32 s9, 0, 0x14000
	v_add_u32_e32 v54, s11, v193
	v_add_u32_e32 v150, s9, v193
	ds_read_b128 v[34:37], v54
	ds_read_b128 v[38:41], v54 offset:1024
	ds_read_b128 v[50:53], v54 offset:2048
	ds_read_b128 v[54:57], v54 offset:3072
	ds_read_b128 v[114:117], v150
	ds_read_b128 v[126:129], v150 offset:1024
	ds_read_b128 v[138:141], v150 offset:2048
	ds_read_b128 v[150:153], v150 offset:3072
	s_add_i32 m0, s66, 0xc000
	ds_read_b128 v[154:157], v217
	ds_read_b128 v[158:161], v217 offset:1024
	ds_read_b128 v[170:173], v217 offset:2048
	ds_read_b128 v[206:209], v217 offset:3072
	ds_read_b128 v[210:213], v217 offset:4096
	ds_read_b128 v[218:221], v217 offset:5120
	ds_read_b128 v[236:239], v217 offset:6144
	ds_read_b128 v[240:243], v217 offset:7168
	global_load_lds_dwordx4 v180, s[68:69]
	s_add_i32 m0, s66, 0xe000
	s_nop 0
	global_load_lds_dwordx4 v182, s[68:69]
	s_waitcnt vmcnt(8)
	s_waitcnt lgkmcnt(0)
	s_barrier
	v_mfma_f32_16x16x32_bf16 v[166:169], v[34:37], v[154:157], v[166:169]
	v_mfma_f32_16x16x32_bf16 v[162:165], v[50:53], v[154:157], v[162:165]
	v_mfma_f32_16x16x32_bf16 v[134:137], v[34:37], v[170:173], v[134:137]
	v_mfma_f32_16x16x32_bf16 v[130:133], v[50:53], v[170:173], v[130:133]
	v_mfma_f32_16x16x32_bf16 v[110:113], v[34:37], v[210:213], v[110:113]
	v_mfma_f32_16x16x32_bf16 v[106:109], v[50:53], v[210:213], v[106:109]
	v_mfma_f32_16x16x32_bf16 v[94:97], v[34:37], v[236:239], v[94:97]
	v_mfma_f32_16x16x32_bf16 v[90:93], v[50:53], v[236:239], v[90:93]
	v_mfma_f32_16x16x32_bf16 v[166:169], v[38:41], v[158:161], v[166:169]
	v_mfma_f32_16x16x32_bf16 v[162:165], v[54:57], v[158:161], v[162:165]
	v_mfma_f32_16x16x32_bf16 v[134:137], v[38:41], v[206:209], v[134:137]
	v_mfma_f32_16x16x32_bf16 v[130:133], v[54:57], v[206:209], v[130:133]
	v_mfma_f32_16x16x32_bf16 v[110:113], v[38:41], v[218:221], v[110:113]
	v_mfma_f32_16x16x32_bf16 v[106:109], v[54:57], v[218:221], v[106:109]
	v_mfma_f32_16x16x32_bf16 v[94:97], v[38:41], v[240:243], v[94:97]
	v_mfma_f32_16x16x32_bf16 v[90:93], v[54:57], v[240:243], v[90:93]
	v_mfma_f32_16x16x32_bf16 v[146:149], v[114:117], v[154:157], v[146:149]
	v_mfma_f32_16x16x32_bf16 v[142:145], v[138:141], v[154:157], v[142:145]
	v_mfma_f32_16x16x32_bf16 v[122:125], v[114:117], v[170:173], v[122:125]
	v_mfma_f32_16x16x32_bf16 v[118:121], v[138:141], v[170:173], v[118:121]
	v_mfma_f32_16x16x32_bf16 v[102:105], v[114:117], v[210:213], v[102:105]
	v_mfma_f32_16x16x32_bf16 v[98:101], v[138:141], v[210:213], v[98:101]
	v_mfma_f32_16x16x32_bf16 v[86:89], v[114:117], v[236:239], v[86:89]
	v_mfma_f32_16x16x32_bf16 v[82:85], v[138:141], v[236:239], v[82:85]
	v_mfma_f32_16x16x32_bf16 v[146:149], v[126:129], v[158:161], v[146:149]
	v_mfma_f32_16x16x32_bf16 v[142:145], v[150:153], v[158:161], v[142:145]
	v_mfma_f32_16x16x32_bf16 v[122:125], v[126:129], v[206:209], v[122:125]
	v_mfma_f32_16x16x32_bf16 v[118:121], v[150:153], v[206:209], v[118:121]
	v_mfma_f32_16x16x32_bf16 v[102:105], v[126:129], v[218:221], v[102:105]
	v_mfma_f32_16x16x32_bf16 v[98:101], v[150:153], v[218:221], v[98:101]
	v_mfma_f32_16x16x32_bf16 v[86:89], v[126:129], v[240:243], v[86:89]
	v_mfma_f32_16x16x32_bf16 v[82:85], v[150:153], v[240:243], v[82:85]
	s_add_i32 s10, s11, s25
	s_mov_b32 m0, s10
	s_barrier
	ds_read_b128 v[154:157], v217 offset:16384
	ds_read_b128 v[158:161], v217 offset:17408
	ds_read_b128 v[170:173], v217 offset:18432
	ds_read_b128 v[206:209], v217 offset:19456
	ds_read_b128 v[210:213], v217 offset:20480
	ds_read_b128 v[218:221], v217 offset:21504
	ds_read_b128 v[236:239], v217 offset:22528
	ds_read_b128 v[240:243], v217 offset:23552
	global_load_lds_dwordx4 v190, s[72:73]
	s_add_i32 m0, s10, 0x2000
	s_add_u32 s10, s72, 0x8000
	s_addc_u32 s11, s73, 0
	s_add_i32 s9, s9, s25
	global_load_lds_dwordx4 v174, s[72:73]
	s_mov_b32 m0, s9
	s_nop 0
	global_load_lds_dwordx4 v190, s[10:11]
	s_add_i32 m0, s9, 0x2000
	s_nop 0
	global_load_lds_dwordx4 v174, s[10:11]
	s_mov_b32 m0, s66
	s_nop 0
	global_load_lds_dwordx4 v178, s[76:77]
	s_mov_b32 m0, s67
	s_nop 0
	global_load_lds_dwordx4 v176, s[76:77]
	s_waitcnt vmcnt(8)
	s_waitcnt lgkmcnt(0)
	s_barrier
	v_mfma_f32_16x16x32_bf16 v[78:81], v[34:37], v[154:157], v[78:81]
	v_mfma_f32_16x16x32_bf16 v[74:77], v[50:53], v[154:157], v[74:77]
	v_mfma_f32_16x16x32_bf16 v[62:65], v[34:37], v[170:173], v[62:65]
	v_mfma_f32_16x16x32_bf16 v[58:61], v[50:53], v[170:173], v[58:61]
	v_mfma_f32_16x16x32_bf16 v[30:33], v[34:37], v[210:213], v[30:33]
	v_mfma_f32_16x16x32_bf16 v[26:29], v[50:53], v[210:213], v[26:29]
	v_mfma_f32_16x16x32_bf16 v[14:17], v[34:37], v[236:239], v[14:17]
	v_mfma_f32_16x16x32_bf16 v[10:13], v[50:53], v[236:239], v[10:13]
	v_mfma_f32_16x16x32_bf16 v[78:81], v[38:41], v[158:161], v[78:81]
	v_mfma_f32_16x16x32_bf16 v[74:77], v[54:57], v[158:161], v[74:77]
	v_mfma_f32_16x16x32_bf16 v[62:65], v[38:41], v[206:209], v[62:65]
	v_mfma_f32_16x16x32_bf16 v[58:61], v[54:57], v[206:209], v[58:61]
	v_mfma_f32_16x16x32_bf16 v[30:33], v[38:41], v[218:221], v[30:33]
	v_mfma_f32_16x16x32_bf16 v[26:29], v[54:57], v[218:221], v[26:29]
	v_mfma_f32_16x16x32_bf16 v[14:17], v[38:41], v[240:243], v[14:17]
	v_mfma_f32_16x16x32_bf16 v[10:13], v[54:57], v[240:243], v[10:13]
	v_mfma_f32_16x16x32_bf16 v[46:49], v[114:117], v[170:173], v[46:49]
	v_mfma_f32_16x16x32_bf16 v[42:45], v[138:141], v[170:173], v[42:45]
	v_mfma_f32_16x16x32_bf16 v[22:25], v[114:117], v[210:213], v[22:25]
	v_mfma_f32_16x16x32_bf16 v[18:21], v[138:141], v[210:213], v[18:21]
	v_mfma_f32_16x16x32_bf16 v[6:9], v[114:117], v[236:239], v[6:9]
	v_mfma_f32_16x16x32_bf16 v[2:5], v[138:141], v[236:239], v[2:5]
	v_mfma_f32_16x16x32_bf16 v[34:37], v[114:117], v[154:157], v[70:73]
	v_mfma_f32_16x16x32_bf16 v[38:41], v[138:141], v[154:157], v[66:69]
	v_mfma_f32_16x16x32_bf16 v[46:49], v[126:129], v[206:209], v[46:49]
	v_mfma_f32_16x16x32_bf16 v[42:45], v[150:153], v[206:209], v[42:45]
	v_mfma_f32_16x16x32_bf16 v[22:25], v[126:129], v[218:221], v[22:25]
	v_mfma_f32_16x16x32_bf16 v[18:21], v[150:153], v[218:221], v[18:21]
	v_mfma_f32_16x16x32_bf16 v[6:9], v[126:129], v[240:243], v[6:9]
	v_mfma_f32_16x16x32_bf16 v[2:5], v[150:153], v[240:243], v[2:5]
	v_mfma_f32_16x16x32_bf16 v[34:37], v[126:129], v[158:161], v[34:37]
	v_mfma_f32_16x16x32_bf16 v[38:41], v[150:153], v[158:161], v[38:41]
	s_add_i32 s9, 0, 0x18000
	s_add_i32 s12, 0, 0x1c000
	s_barrier
; #define PG8_STAGE(bufoff, gbase, voff) do { _Pragma("unroll") for (int _i = 0; _i < 2; ++_i) \
;         __builtin_amdgcn_global_load_lds((const unsigned*)((const char*)(gbase) + (voff)[_i]), (PG8_LAS unsigned*)(lds + (bufoff) + ldsw + _i * 8192), 16, 0, 0); } while (0)
; #define PG8_LDA(dst, b, h) do { _Pragma("unroll") for (int m = 0; m < 4; ++m) _Pragma("unroll") for (int k = 0; k < 2; ++k) dst[m][k] = *(const PG8_LAS bf16x8*)(lds + PG8_SA(b, h) + aoff + m * 2048 + k * 1024); } while (0)
; #define PG8_LDB(dst, b, h) do { _Pragma("unroll") for (int n = 0; n < 2; ++n) _Pragma("unroll") for (int k = 0; k < 2; ++k) dst[n][k] = *(const PG8_LAS bf16x8*)(lds + PG8_SB(b, h) + boff + n * 2048 + k * 1024); } while (0)
; #define PG8_MMA(ai, bj, At, Bt) do { __builtin_amdgcn_s_setprio(1); _Pragma("unroll") for (int m = 0; m < 4; ++m) _Pragma("unroll") for (int n = 0; n < 2; ++n) _Pragma("unroll") for (int k = 0; k < 2; ++k) \
;         acc[ai][bj][m][n] = __builtin_amdgcn_mfma_f32_16x16x32_bf16(Bt[n][k], At[m][k], acc[ai][bj][m][n], 0, 0, 0); __builtin_amdgcn_s_setprio(0); } while (0)
; #define PG8_WAIT_V(n) asm volatile("s_waitcnt vmcnt(" #n ")" ::: "memory")
; #define PG8_WAIT_L(n) asm volatile("s_waitcnt lgkmcnt(" #n ")" ::: "memory")
; #define PG8_BAR __builtin_amdgcn_s_barrier()
; #define PG8_SCHED __builtin_amdgcn_sched_barrier(0)
; template <class Epi, class Sched, bool ALIGN_EPI = false, bool SP2 = false>
; __device__ __forceinline__ void gemm_phase(PG8_LAS unsigned char* lds, const Gemm g, const Sched& S, const Epi& E) {
;     ...
;             PG8_LDB(B0, 1, 0); PG8_LDB(B1, 1, 1); PG8_SCHED; PG8_LDA(At, 1, 0); PG8_STAGE(PG8_SA(0, 1), a2 + hstep, voffA);
;             PG8_WAIT_V(8); PG8_WAIT_L(0); PG8_BAR; PG8_MMA(0, 0, At, B0); PG8_MMA(0, 1, At, B1); PG8_BAR; PG8_SCHED;
;             PG8_LDA(At, 1, 1); PG8_STAGE(PG8_SB(1, 0), b3, voffB); PG8_STAGE(PG8_SB(1, 1), b3 + hstepB, voffB); PG8_STAGE(PG8_SA(1, 0), a3, voffA);
;             PG8_WAIT_V(8); PG8_WAIT_L(0); PG8_BAR; PG8_MMA(1, 0, At, B0); PG8_MMA(1, 1, At, B1); PG8_BAR; PG8_SCHED;
	v_add_u32_e32 v70, s9, v193
	v_add_u32_e32 v150, s12, v193
	ds_read_b128 v[50:53], v70
	ds_read_b128 v[54:57], v70 offset:1024
	ds_read_b128 v[66:69], v70 offset:2048
	ds_read_b128 v[70:73], v70 offset:3072
	ds_read_b128 v[114:117], v150
	ds_read_b128 v[126:129], v150 offset:1024
	ds_read_b128 v[138:141], v150 offset:2048
	ds_read_b128 v[150:153], v150 offset:3072
	s_add_u32 s10, s76, 0x20000
	s_addc_u32 s11, s77, 0
	s_mov_b32 m0, s80
	ds_read_b128 v[154:157], v217 offset:32768
	ds_read_b128 v[158:161], v217 offset:33792
	ds_read_b128 v[170:173], v217 offset:34816
	ds_read_b128 v[206:209], v217 offset:35840
	ds_read_b128 v[210:213], v217 offset:36864
	ds_read_b128 v[218:221], v217 offset:37888
	ds_read_b128 v[236:239], v217 offset:38912
	ds_read_b128 v[240:243], v217 offset:39936
	global_load_lds_dwordx4 v178, s[10:11]
	s_mov_b32 m0, s81
	s_nop 0
	global_load_lds_dwordx4 v176, s[10:11]
	s_waitcnt vmcnt(8)
	s_waitcnt lgkmcnt(0)
	s_barrier
	v_mfma_f32_16x16x32_bf16 v[166:169], v[50:53], v[154:157], v[166:169]
	v_mfma_f32_16x16x32_bf16 v[162:165], v[66:69], v[154:157], v[162:165]
	v_mfma_f32_16x16x32_bf16 v[134:137], v[50:53], v[170:173], v[134:137]
	v_mfma_f32_16x16x32_bf16 v[130:133], v[66:69], v[170:173], v[130:133]
	v_mfma_f32_16x16x32_bf16 v[110:113], v[50:53], v[210:213], v[110:113]
	v_mfma_f32_16x16x32_bf16 v[106:109], v[66:69], v[210:213], v[106:109]
	v_mfma_f32_16x16x32_bf16 v[94:97], v[50:53], v[236:239], v[94:97]
	v_mfma_f32_16x16x32_bf16 v[90:93], v[66:69], v[236:239], v[90:93]
	v_mfma_f32_16x16x32_bf16 v[166:169], v[54:57], v[158:161], v[166:169]
	v_mfma_f32_16x16x32_bf16 v[162:165], v[70:73], v[158:161], v[162:165]
	v_mfma_f32_16x16x32_bf16 v[134:137], v[54:57], v[206:209], v[134:137]
	v_mfma_f32_16x16x32_bf16 v[130:133], v[70:73], v[206:209], v[130:133]
	v_mfma_f32_16x16x32_bf16 v[110:113], v[54:57], v[218:221], v[110:113]
	v_mfma_f32_16x16x32_bf16 v[106:109], v[70:73], v[218:221], v[106:109]
	v_mfma_f32_16x16x32_bf16 v[94:97], v[54:57], v[240:243], v[94:97]
	v_mfma_f32_16x16x32_bf16 v[90:93], v[70:73], v[240:243], v[90:93]
	v_mfma_f32_16x16x32_bf16 v[146:149], v[114:117], v[154:157], v[146:149]
	v_mfma_f32_16x16x32_bf16 v[142:145], v[138:141], v[154:157], v[142:145]
	v_mfma_f32_16x16x32_bf16 v[122:125], v[114:117], v[170:173], v[122:125]
	v_mfma_f32_16x16x32_bf16 v[118:121], v[138:141], v[170:173], v[118:121]
	v_mfma_f32_16x16x32_bf16 v[102:105], v[114:117], v[210:213], v[102:105]
	v_mfma_f32_16x16x32_bf16 v[98:101], v[138:141], v[210:213], v[98:101]
	v_mfma_f32_16x16x32_bf16 v[86:89], v[114:117], v[236:239], v[86:89]
	v_mfma_f32_16x16x32_bf16 v[82:85], v[138:141], v[236:239], v[82:85]
	v_mfma_f32_16x16x32_bf16 v[146:149], v[126:129], v[158:161], v[146:149]
	v_mfma_f32_16x16x32_bf16 v[142:145], v[150:153], v[158:161], v[142:145]
	v_mfma_f32_16x16x32_bf16 v[122:125], v[126:129], v[206:209], v[122:125]
	v_mfma_f32_16x16x32_bf16 v[118:121], v[150:153], v[206:209], v[118:121]
	v_mfma_f32_16x16x32_bf16 v[102:105], v[126:129], v[218:221], v[102:105]
	v_mfma_f32_16x16x32_bf16 v[98:101], v[150:153], v[218:221], v[98:101]
	v_mfma_f32_16x16x32_bf16 v[86:89], v[126:129], v[240:243], v[86:89]
	v_mfma_f32_16x16x32_bf16 v[82:85], v[150:153], v[240:243], v[82:85]
	s_add_i32 s9, s9, s25
	s_mov_b32 m0, s9
	s_barrier
	ds_read_b128 v[154:157], v217 offset:49152
	ds_read_b128 v[158:161], v217 offset:50176
	ds_read_b128 v[170:173], v217 offset:51200
	ds_read_b128 v[206:209], v217 offset:52224
	ds_read_b128 v[210:213], v217 offset:53248
	ds_read_b128 v[218:221], v217 offset:54272
	ds_read_b128 v[236:239], v217 offset:55296
	ds_read_b128 v[240:243], v217 offset:56320
	s_add_u32 s100, s72, s60
	s_addc_u32 s101, s73, s61
	global_load_lds_dwordx4 v190, s[100:101]
	s_add_i32 m0, s9, 0x2000
	s_add_u32 s10, s72, 0x8080
	s_addc_u32 s11, s73, 0
	s_add_i32 s9, s12, s25
	global_load_lds_dwordx4 v174, s[100:101]
	s_mov_b32 m0, s9
	s_nop 0
	global_load_lds_dwordx4 v190, s[10:11]
	s_add_i32 m0, s9, 0x2000
	s_nop 0
	global_load_lds_dwordx4 v174, s[10:11]
	s_mov_b32 m0, s82
	s_add_u32 s100, s76, s60
	s_addc_u32 s101, s77, s61
	global_load_lds_dwordx4 v178, s[100:101]
	s_mov_b32 m0, s92
	s_nop 0
	global_load_lds_dwordx4 v176, s[100:101]
	s_waitcnt vmcnt(8)
	s_waitcnt lgkmcnt(0)
	s_barrier
	v_mfma_f32_16x16x32_bf16 v[78:81], v[50:53], v[154:157], v[78:81]
	v_mfma_f32_16x16x32_bf16 v[74:77], v[66:69], v[154:157], v[74:77]
	v_mfma_f32_16x16x32_bf16 v[62:65], v[50:53], v[170:173], v[62:65]
	v_mfma_f32_16x16x32_bf16 v[58:61], v[66:69], v[170:173], v[58:61]
	v_mfma_f32_16x16x32_bf16 v[30:33], v[50:53], v[210:213], v[30:33]
	v_mfma_f32_16x16x32_bf16 v[26:29], v[66:69], v[210:213], v[26:29]
	v_mfma_f32_16x16x32_bf16 v[14:17], v[50:53], v[236:239], v[14:17]
	v_mfma_f32_16x16x32_bf16 v[10:13], v[66:69], v[236:239], v[10:13]
	v_mfma_f32_16x16x32_bf16 v[78:81], v[54:57], v[158:161], v[78:81]
	v_mfma_f32_16x16x32_bf16 v[74:77], v[70:73], v[158:161], v[74:77]
	v_mfma_f32_16x16x32_bf16 v[62:65], v[54:57], v[206:209], v[62:65]
	v_mfma_f32_16x16x32_bf16 v[58:61], v[70:73], v[206:209], v[58:61]
	v_mfma_f32_16x16x32_bf16 v[30:33], v[54:57], v[218:221], v[30:33]
	v_mfma_f32_16x16x32_bf16 v[26:29], v[70:73], v[218:221], v[26:29]
	v_mfma_f32_16x16x32_bf16 v[14:17], v[54:57], v[240:243], v[14:17]
	v_mfma_f32_16x16x32_bf16 v[10:13], v[70:73], v[240:243], v[10:13]
	v_mfma_f32_16x16x32_bf16 v[34:37], v[114:117], v[154:157], v[34:37]
	v_mfma_f32_16x16x32_bf16 v[70:73], v[126:129], v[158:161], v[34:37]
	v_mfma_f32_16x16x32_bf16 v[34:37], v[138:141], v[154:157], v[38:41]
	v_mfma_f32_16x16x32_bf16 v[66:69], v[150:153], v[158:161], v[34:37]
	v_mfma_f32_16x16x32_bf16 v[34:37], v[114:117], v[170:173], v[46:49]
	v_mfma_f32_16x16x32_bf16 v[46:49], v[126:129], v[206:209], v[34:37]
	v_mfma_f32_16x16x32_bf16 v[34:37], v[138:141], v[170:173], v[42:45]
	v_mfma_f32_16x16x32_bf16 v[22:25], v[114:117], v[210:213], v[22:25]
	v_mfma_f32_16x16x32_bf16 v[18:21], v[138:141], v[210:213], v[18:21]
	v_mfma_f32_16x16x32_bf16 v[6:9], v[114:117], v[236:239], v[6:9]
	v_mfma_f32_16x16x32_bf16 v[2:5], v[138:141], v[236:239], v[2:5]
	v_mfma_f32_16x16x32_bf16 v[42:45], v[150:153], v[206:209], v[34:37]
	v_mfma_f32_16x16x32_bf16 v[22:25], v[126:129], v[218:221], v[22:25]
	v_mfma_f32_16x16x32_bf16 v[18:21], v[150:153], v[218:221], v[18:21]
	v_mfma_f32_16x16x32_bf16 v[6:9], v[126:129], v[240:243], v[6:9]
	v_mfma_f32_16x16x32_bf16 v[2:5], v[150:153], v[240:243], v[2:5]
	s_add_i32 s8, s8, 2
	s_add_u32 s68, s68, 0x100
	s_addc_u32 s69, s69, 0
	s_add_u32 s6, s6, 0x100
	s_addc_u32 s7, s7, 0
	s_cmp_gt_u32 s8, 5
	s_barrier
	s_cbranch_scc0 .LBB0_788
	s_and_b64 vcc, exec, s[46:47]
	s_cbranch_vccz .LBB0_791
	s_barrier

; #define PG8_STAGE(bufoff, gbase, voff) do { _Pragma("unroll") for (int _i = 0; _i < 2; ++_i) \
;         __builtin_amdgcn_global_load_lds((const unsigned*)((const char*)(gbase) + (voff)[_i]), (PG8_LAS unsigned*)(lds + (bufoff) + ldsw + _i * 8192), 16, 0, 0); } while (0)
; #define PG8_LDA(dst, b, h) do { _Pragma("unroll") for (int m = 0; m < 4; ++m) _Pragma("unroll") for (int k = 0; k < 2; ++k) dst[m][k] = *(const PG8_LAS bf16x8*)(lds + PG8_SA(b, h) + aoff + m * 2048 + k * 1024); } while (0)
; #define PG8_LDB(dst, b, h) do { _Pragma("unroll") for (int n = 0; n < 2; ++n) _Pragma("unroll") for (int k = 0; k < 2; ++k) dst[n][k] = *(const PG8_LAS bf16x8*)(lds + PG8_SB(b, h) + boff + n * 2048 + k * 1024); } while (0)
; #define PG8_MMA(ai, bj, At, Bt) do { __builtin_amdgcn_s_setprio(1); _Pragma("unroll") for (int m = 0; m < 4; ++m) _Pragma("unroll") for (int n = 0; n < 2; ++n) _Pragma("unroll") for (int k = 0; k < 2; ++k) \
;         acc[ai][bj][m][n] = __builtin_amdgcn_mfma_f32_16x16x32_bf16(Bt[n][k], At[m][k], acc[ai][bj][m][n], 0, 0, 0); __builtin_amdgcn_s_setprio(0); } while (0)
; #define PG8_BAR __builtin_amdgcn_s_barrier()
; template <class Epi, class Sched, bool ALIGN_EPI = false, bool SP2 = false>
; __device__ __forceinline__ void gemm_phase(PG8_LAS unsigned char* lds, const Gemm g, const Sched& S, const Epi& E) {
;     ...
;             const bool last = (t == nt - 2);
;             const char* a1 = cA + (size_t)(t + 1) * kstep;
;             const char* a2 = last ? nA : cA + (size_t)(t + 2) * kstep; const char* b2 = last ? nB : cB + (size_t)(t + 2) * kstep;
;             const char* a3 = a2 + kstep; const char* b3 = b2 + kstep;
;             if (last && has_next) S.a_ready(nxt);
;             if constexpr (SP2) {
;             PG8_LDB(B0, 0, 0); PG8_LDB(B1, 0, 1); PG8_SCHED; PG8_LDA(At, 0, 0); PG8_STAGE(PG8_SA(1, 1), a1 + hstep, voffA);
;             PG8_WAIT_V(8); PG8_WAIT_L(0); PG8_BAR; PG8_MMA(0, 0, At, B0); PG8_MMA(0, 1, At, B1); PG8_BAR; PG8_SCHED;
;             PG8_LDA(At, 0, 1); PG8_STAGE(PG8_SB(0, 0), b2, voffB); PG8_STAGE(PG8_SB(0, 1), b2 + hstepB, voffB); PG8_STAGE(PG8_SA(0, 0), a2, voffA);
;             PG8_WAIT_V(8); PG8_WAIT_L(0); PG8_BAR; PG8_MMA(1, 0, At, B0); PG8_MMA(1, 1, At, B1); PG8_BAR; PG8_SCHED;
;             PG8_LDB(B0, 1, 0); PG8_LDB(B1, 1, 1); PG8_SCHED; PG8_LDA(At, 1, 0); PG8_STAGE(PG8_SA(0, 1), a2 + hstep, voffA);
.LBB0_927:
	s_add_u32 s9, s38, 0xfff80080
	s_addc_u32 s10, s39, -1
	s_add_i32 s11, 0, 0x10000
	s_cmp_eq_u32 s8, 28
	s_cselect_b32 s95, s36, s10
	s_cselect_b32 s94, s37, s9
	s_cselect_b32 s47, s4, s7
	s_cselect_b32 s46, s5, s6
	s_add_i32 s9, 0, 0x14000
	v_add_u32_e32 v86, s11, v193
	v_add_u32_e32 v158, s9, v193
	ds_read_b128 v[66:69], v86
	ds_read_b128 v[70:73], v86 offset:1024
	ds_read_b128 v[78:81], v86 offset:2048
	ds_read_b128 v[86:89], v86 offset:3072
	ds_read_b128 v[146:149], v158
	ds_read_b128 v[150:153], v158 offset:1024
	ds_read_b128 v[154:157], v158 offset:2048
	ds_read_b128 v[158:161], v158 offset:3072
	s_add_i32 m0, s66, 0xc000
	ds_read_b128 v[162:165], v236
	ds_read_b128 v[166:169], v236 offset:1024
	ds_read_b128 v[170:173], v236 offset:2048
	ds_read_b128 v[174:177], v236 offset:3072
	ds_read_b128 v[178:181], v236 offset:4096
	ds_read_b128 v[182:185], v236 offset:5120
	ds_read_b128 v[216:219], v236 offset:6144
	ds_read_b128 v[220:223], v236 offset:7168
	global_load_lds_dwordx4 v212, s[38:39]
	s_add_i32 m0, s66, 0xe000
	s_nop 0
	global_load_lds_dwordx4 v214, s[38:39]
	s_waitcnt vmcnt(8)
	s_waitcnt lgkmcnt(0)
	s_barrier
	v_mfma_f32_16x16x32_bf16 v[142:145], v[66:69], v[162:165], v[142:145]
	v_mfma_f32_16x16x32_bf16 v[138:141], v[78:81], v[162:165], v[138:141]
	v_mfma_f32_16x16x32_bf16 v[126:129], v[66:69], v[170:173], v[126:129]
	v_mfma_f32_16x16x32_bf16 v[122:125], v[78:81], v[170:173], v[122:125]
	v_mfma_f32_16x16x32_bf16 v[110:113], v[66:69], v[178:181], v[110:113]
	v_mfma_f32_16x16x32_bf16 v[106:109], v[78:81], v[178:181], v[106:109]
	v_mfma_f32_16x16x32_bf16 v[94:97], v[66:69], v[216:219], v[94:97]
	v_mfma_f32_16x16x32_bf16 v[90:93], v[78:81], v[216:219], v[90:93]
	v_mfma_f32_16x16x32_bf16 v[142:145], v[70:73], v[166:169], v[142:145]
	v_mfma_f32_16x16x32_bf16 v[138:141], v[86:89], v[166:169], v[138:141]
	v_mfma_f32_16x16x32_bf16 v[126:129], v[70:73], v[174:177], v[126:129]
	v_mfma_f32_16x16x32_bf16 v[122:125], v[86:89], v[174:177], v[122:125]
	v_mfma_f32_16x16x32_bf16 v[110:113], v[70:73], v[182:185], v[110:113]
	v_mfma_f32_16x16x32_bf16 v[106:109], v[86:89], v[182:185], v[106:109]
	v_mfma_f32_16x16x32_bf16 v[94:97], v[70:73], v[220:223], v[94:97]
	v_mfma_f32_16x16x32_bf16 v[90:93], v[86:89], v[220:223], v[90:93]
	v_mfma_f32_16x16x32_bf16 v[134:137], v[146:149], v[162:165], v[134:137]
	v_mfma_f32_16x16x32_bf16 v[130:133], v[154:157], v[162:165], v[130:133]
	v_mfma_f32_16x16x32_bf16 v[118:121], v[146:149], v[170:173], v[118:121]
	v_mfma_f32_16x16x32_bf16 v[114:117], v[154:157], v[170:173], v[114:117]
	v_mfma_f32_16x16x32_bf16 v[102:105], v[146:149], v[178:181], v[102:105]
	v_mfma_f32_16x16x32_bf16 v[98:101], v[154:157], v[178:181], v[98:101]
	v_mfma_f32_16x16x32_bf16 v[82:85], v[146:149], v[216:219], v[82:85]
	v_mfma_f32_16x16x32_bf16 v[74:77], v[154:157], v[216:219], v[74:77]
	v_mfma_f32_16x16x32_bf16 v[134:137], v[150:153], v[166:169], v[134:137]
	v_mfma_f32_16x16x32_bf16 v[130:133], v[158:161], v[166:169], v[130:133]
	v_mfma_f32_16x16x32_bf16 v[118:121], v[150:153], v[174:177], v[118:121]
	v_mfma_f32_16x16x32_bf16 v[114:117], v[158:161], v[174:177], v[114:117]
	v_mfma_f32_16x16x32_bf16 v[102:105], v[150:153], v[182:185], v[102:105]
	v_mfma_f32_16x16x32_bf16 v[98:101], v[158:161], v[182:185], v[98:101]
	v_mfma_f32_16x16x32_bf16 v[82:85], v[150:153], v[220:223], v[82:85]
	v_mfma_f32_16x16x32_bf16 v[74:77], v[158:161], v[220:223], v[74:77]
	s_add_i32 s10, s11, s25
	s_mov_b32 m0, s10
	s_barrier
	ds_read_b128 v[162:165], v236 offset:16384
	ds_read_b128 v[166:169], v236 offset:17408
	ds_read_b128 v[170:173], v236 offset:18432
	ds_read_b128 v[174:177], v236 offset:19456
	ds_read_b128 v[178:181], v236 offset:20480
	ds_read_b128 v[182:185], v236 offset:21504
	ds_read_b128 v[216:219], v236 offset:22528
	ds_read_b128 v[220:223], v236 offset:23552
	global_load_lds_dwordx4 v190, s[46:47]
	s_add_i32 m0, s10, 0x2000
	s_add_u32 s10, s46, 0x20000
	s_addc_u32 s11, s47, 0
	s_add_i32 s9, s9, s25
	global_load_lds_dwordx4 v206, s[46:47]
	s_mov_b32 m0, s9
	s_nop 0
	global_load_lds_dwordx4 v190, s[10:11]
	s_add_i32 m0, s9, 0x2000
	s_nop 0
	global_load_lds_dwordx4 v206, s[10:11]
	s_mov_b32 m0, s66
	s_nop 0
	global_load_lds_dwordx4 v210, s[94:95]
	s_mov_b32 m0, s67
	s_nop 0
	global_load_lds_dwordx4 v208, s[94:95]
	s_waitcnt vmcnt(8)
	s_waitcnt lgkmcnt(0)
	s_barrier
	v_mfma_f32_16x16x32_bf16 v[62:65], v[66:69], v[162:165], v[62:65]
	v_mfma_f32_16x16x32_bf16 v[58:61], v[78:81], v[162:165], v[58:61]
	v_mfma_f32_16x16x32_bf16 v[46:49], v[66:69], v[170:173], v[46:49]
	v_mfma_f32_16x16x32_bf16 v[42:45], v[78:81], v[170:173], v[42:45]
	v_mfma_f32_16x16x32_bf16 v[30:33], v[66:69], v[178:181], v[30:33]
	v_mfma_f32_16x16x32_bf16 v[26:29], v[78:81], v[178:181], v[26:29]
	v_mfma_f32_16x16x32_bf16 v[14:17], v[66:69], v[216:219], v[14:17]
	v_mfma_f32_16x16x32_bf16 v[10:13], v[78:81], v[216:219], v[10:13]
	v_mfma_f32_16x16x32_bf16 v[62:65], v[70:73], v[166:169], v[62:65]
	v_mfma_f32_16x16x32_bf16 v[58:61], v[86:89], v[166:169], v[58:61]
	v_mfma_f32_16x16x32_bf16 v[46:49], v[70:73], v[174:177], v[46:49]
	v_mfma_f32_16x16x32_bf16 v[42:45], v[86:89], v[174:177], v[42:45]
	v_mfma_f32_16x16x32_bf16 v[30:33], v[70:73], v[182:185], v[30:33]
	v_mfma_f32_16x16x32_bf16 v[26:29], v[86:89], v[182:185], v[26:29]
	v_mfma_f32_16x16x32_bf16 v[14:17], v[70:73], v[220:223], v[14:17]
	v_mfma_f32_16x16x32_bf16 v[10:13], v[86:89], v[220:223], v[10:13]
	v_mfma_f32_16x16x32_bf16 v[54:57], v[146:149], v[162:165], v[54:57]
	v_mfma_f32_16x16x32_bf16 v[50:53], v[154:157], v[162:165], v[50:53]
	v_mfma_f32_16x16x32_bf16 v[38:41], v[146:149], v[170:173], v[38:41]
	v_mfma_f32_16x16x32_bf16 v[34:37], v[154:157], v[170:173], v[34:37]
	v_mfma_f32_16x16x32_bf16 v[22:25], v[146:149], v[178:181], v[22:25]
	v_mfma_f32_16x16x32_bf16 v[18:21], v[154:157], v[178:181], v[18:21]
	v_mfma_f32_16x16x32_bf16 v[6:9], v[146:149], v[216:219], v[6:9]
	v_mfma_f32_16x16x32_bf16 v[2:5], v[154:157], v[216:219], v[2:5]
	v_mfma_f32_16x16x32_bf16 v[54:57], v[150:153], v[166:169], v[54:57]
	v_mfma_f32_16x16x32_bf16 v[50:53], v[158:161], v[166:169], v[50:53]
	v_mfma_f32_16x16x32_bf16 v[38:41], v[150:153], v[174:177], v[38:41]
	v_mfma_f32_16x16x32_bf16 v[34:37], v[158:161], v[174:177], v[34:37]
	v_mfma_f32_16x16x32_bf16 v[22:25], v[150:153], v[182:185], v[22:25]
	v_mfma_f32_16x16x32_bf16 v[18:21], v[158:161], v[182:185], v[18:21]
	v_mfma_f32_16x16x32_bf16 v[6:9], v[150:153], v[220:223], v[6:9]
	v_mfma_f32_16x16x32_bf16 v[2:5], v[158:161], v[220:223], v[2:5]
	s_add_i32 s9, 0, 0x18000
	s_add_i32 s12, 0, 0x1c000
	s_barrier
; #define PG8_STAGE(bufoff, gbase, voff) do { _Pragma("unroll") for (int _i = 0; _i < 2; ++_i) \
;         __builtin_amdgcn_global_load_lds((const unsigned*)((const char*)(gbase) + (voff)[_i]), (PG8_LAS unsigned*)(lds + (bufoff) + ldsw + _i * 8192), 16, 0, 0); } while (0)
; #define PG8_LDA(dst, b, h) do { _Pragma("unroll") for (int m = 0; m < 4; ++m) _Pragma("unroll") for (int k = 0; k < 2; ++k) dst[m][k] = *(const PG8_LAS bf16x8*)(lds + PG8_SA(b, h) + aoff + m * 2048 + k * 1024); } while (0)
; #define PG8_LDB(dst, b, h) do { _Pragma("unroll") for (int n = 0; n < 2; ++n) _Pragma("unroll") for (int k = 0; k < 2; ++k) dst[n][k] = *(const PG8_LAS bf16x8*)(lds + PG8_SB(b, h) + boff + n * 2048 + k * 1024); } while (0)
; #define PG8_MMA(ai, bj, At, Bt) do { __builtin_amdgcn_s_setprio(1); _Pragma("unroll") for (int m = 0; m < 4; ++m) _Pragma("unroll") for (int n = 0; n < 2; ++n) _Pragma("unroll") for (int k = 0; k < 2; ++k) \
;         acc[ai][bj][m][n] = __builtin_amdgcn_mfma_f32_16x16x32_bf16(Bt[n][k], At[m][k], acc[ai][bj][m][n], 0, 0, 0); __builtin_amdgcn_s_setprio(0); } while (0)
; #define PG8_WAIT_V(n) asm volatile("s_waitcnt vmcnt(" #n ")" ::: "memory")
; #define PG8_WAIT_L(n) asm volatile("s_waitcnt lgkmcnt(" #n ")" ::: "memory")
; #define PG8_BAR __builtin_amdgcn_s_barrier()
; #define PG8_SCHED __builtin_amdgcn_sched_barrier(0)
; template <class Epi, class Sched, bool ALIGN_EPI = false, bool SP2 = false>
; __device__ __forceinline__ void gemm_phase(PG8_LAS unsigned char* lds, const Gemm g, const Sched& S, const Epi& E) {
;     ...
;             PG8_LDB(B0, 1, 0); PG8_LDB(B1, 1, 1); PG8_SCHED; PG8_LDA(At, 1, 0); PG8_STAGE(PG8_SA(0, 1), a2 + hstep, voffA);
;             PG8_WAIT_V(8); PG8_WAIT_L(0); PG8_BAR; PG8_MMA(0, 0, At, B0); PG8_MMA(0, 1, At, B1); PG8_BAR; PG8_SCHED;
;             PG8_LDA(At, 1, 1); PG8_STAGE(PG8_SB(1, 0), b3, voffB); PG8_STAGE(PG8_SB(1, 1), b3 + hstepB, voffB); PG8_STAGE(PG8_SA(1, 0), a3, voffA);
;             PG8_WAIT_V(8); PG8_WAIT_L(0); PG8_BAR; PG8_MMA(1, 0, At, B0); PG8_MMA(1, 1, At, B1); PG8_BAR; PG8_SCHED;
	v_add_u32_e32 v86, s9, v193
	v_add_u32_e32 v158, s12, v193
	ds_read_b128 v[66:69], v86
	ds_read_b128 v[70:73], v86 offset:1024
	ds_read_b128 v[78:81], v86 offset:2048
	ds_read_b128 v[86:89], v86 offset:3072
	ds_read_b128 v[146:149], v158
	ds_read_b128 v[150:153], v158 offset:1024
	ds_read_b128 v[154:157], v158 offset:2048
	ds_read_b128 v[158:161], v158 offset:3072
	s_add_u32 s10, s94, 0x80000
	s_addc_u32 s11, s95, 0
	s_mov_b32 m0, s59
	ds_read_b128 v[162:165], v236 offset:32768
	ds_read_b128 v[166:169], v236 offset:33792
	ds_read_b128 v[170:173], v236 offset:34816
	ds_read_b128 v[174:177], v236 offset:35840
	ds_read_b128 v[178:181], v236 offset:36864
	ds_read_b128 v[182:185], v236 offset:37888
	ds_read_b128 v[216:219], v236 offset:38912
	ds_read_b128 v[220:223], v236 offset:39936
	global_load_lds_dwordx4 v210, s[10:11]
	s_mov_b32 m0, s74
	s_nop 0
	global_load_lds_dwordx4 v208, s[10:11]
	s_waitcnt vmcnt(8)
	s_waitcnt lgkmcnt(0)
	s_barrier
	v_mfma_f32_16x16x32_bf16 v[142:145], v[66:69], v[162:165], v[142:145]
	v_mfma_f32_16x16x32_bf16 v[138:141], v[78:81], v[162:165], v[138:141]
	v_mfma_f32_16x16x32_bf16 v[126:129], v[66:69], v[170:173], v[126:129]
	v_mfma_f32_16x16x32_bf16 v[122:125], v[78:81], v[170:173], v[122:125]
	v_mfma_f32_16x16x32_bf16 v[110:113], v[66:69], v[178:181], v[110:113]
	v_mfma_f32_16x16x32_bf16 v[106:109], v[78:81], v[178:181], v[106:109]
	v_mfma_f32_16x16x32_bf16 v[94:97], v[66:69], v[216:219], v[94:97]
	v_mfma_f32_16x16x32_bf16 v[90:93], v[78:81], v[216:219], v[90:93]
	v_mfma_f32_16x16x32_bf16 v[142:145], v[70:73], v[166:169], v[142:145]
	v_mfma_f32_16x16x32_bf16 v[138:141], v[86:89], v[166:169], v[138:141]
	v_mfma_f32_16x16x32_bf16 v[126:129], v[70:73], v[174:177], v[126:129]
	v_mfma_f32_16x16x32_bf16 v[122:125], v[86:89], v[174:177], v[122:125]
	v_mfma_f32_16x16x32_bf16 v[110:113], v[70:73], v[182:185], v[110:113]
	v_mfma_f32_16x16x32_bf16 v[106:109], v[86:89], v[182:185], v[106:109]
	v_mfma_f32_16x16x32_bf16 v[94:97], v[70:73], v[220:223], v[94:97]
	v_mfma_f32_16x16x32_bf16 v[90:93], v[86:89], v[220:223], v[90:93]
	v_mfma_f32_16x16x32_bf16 v[134:137], v[146:149], v[162:165], v[134:137]
	v_mfma_f32_16x16x32_bf16 v[130:133], v[154:157], v[162:165], v[130:133]
	v_mfma_f32_16x16x32_bf16 v[118:121], v[146:149], v[170:173], v[118:121]
	v_mfma_f32_16x16x32_bf16 v[114:117], v[154:157], v[170:173], v[114:117]
	v_mfma_f32_16x16x32_bf16 v[102:105], v[146:149], v[178:181], v[102:105]
	v_mfma_f32_16x16x32_bf16 v[98:101], v[154:157], v[178:181], v[98:101]
	v_mfma_f32_16x16x32_bf16 v[82:85], v[146:149], v[216:219], v[82:85]
	v_mfma_f32_16x16x32_bf16 v[74:77], v[154:157], v[216:219], v[74:77]
	v_mfma_f32_16x16x32_bf16 v[134:137], v[150:153], v[166:169], v[134:137]
	v_mfma_f32_16x16x32_bf16 v[130:133], v[158:161], v[166:169], v[130:133]
	v_mfma_f32_16x16x32_bf16 v[118:121], v[150:153], v[174:177], v[118:121]
	v_mfma_f32_16x16x32_bf16 v[114:117], v[158:161], v[174:177], v[114:117]
	v_mfma_f32_16x16x32_bf16 v[102:105], v[150:153], v[182:185], v[102:105]
	v_mfma_f32_16x16x32_bf16 v[98:101], v[158:161], v[182:185], v[98:101]
	v_mfma_f32_16x16x32_bf16 v[82:85], v[150:153], v[220:223], v[82:85]
	v_mfma_f32_16x16x32_bf16 v[74:77], v[158:161], v[220:223], v[74:77]
	s_add_i32 s9, s9, s25
	s_mov_b32 m0, s9
	s_barrier
	ds_read_b128 v[162:165], v236 offset:49152
	ds_read_b128 v[166:169], v236 offset:50176
	ds_read_b128 v[170:173], v236 offset:51200
	ds_read_b128 v[174:177], v236 offset:52224
	ds_read_b128 v[178:181], v236 offset:53248
	ds_read_b128 v[182:185], v236 offset:54272
	ds_read_b128 v[216:219], v236 offset:55296
	ds_read_b128 v[220:223], v236 offset:56320
	s_add_u32 s100, s46, s60
	s_addc_u32 s101, s47, s61
	global_load_lds_dwordx4 v190, s[100:101]
	s_add_i32 m0, s9, 0x2000
	s_add_u32 s10, s46, 0x20080
	s_addc_u32 s11, s47, 0
	s_add_i32 s9, s12, s25
	global_load_lds_dwordx4 v206, s[100:101]
	s_mov_b32 m0, s9
	s_nop 0
	global_load_lds_dwordx4 v190, s[10:11]
	s_add_i32 m0, s9, 0x2000
	s_nop 0
	global_load_lds_dwordx4 v206, s[10:11]
	s_mov_b32 m0, s75
	s_add_u32 s100, s94, s60
	s_addc_u32 s101, s95, s61
	global_load_lds_dwordx4 v210, s[100:101]
	s_mov_b32 m0, s0
	s_nop 0
	global_load_lds_dwordx4 v208, s[100:101]
	s_waitcnt vmcnt(8)
	s_waitcnt lgkmcnt(0)
	s_barrier
	v_mfma_f32_16x16x32_bf16 v[62:65], v[66:69], v[162:165], v[62:65]
	v_mfma_f32_16x16x32_bf16 v[58:61], v[78:81], v[162:165], v[58:61]
	v_mfma_f32_16x16x32_bf16 v[46:49], v[66:69], v[170:173], v[46:49]
	v_mfma_f32_16x16x32_bf16 v[42:45], v[78:81], v[170:173], v[42:45]
	v_mfma_f32_16x16x32_bf16 v[30:33], v[66:69], v[178:181], v[30:33]
	v_mfma_f32_16x16x32_bf16 v[26:29], v[78:81], v[178:181], v[26:29]
	v_mfma_f32_16x16x32_bf16 v[14:17], v[66:69], v[216:219], v[14:17]
	v_mfma_f32_16x16x32_bf16 v[10:13], v[78:81], v[216:219], v[10:13]
	v_mfma_f32_16x16x32_bf16 v[62:65], v[70:73], v[166:169], v[62:65]
	v_mfma_f32_16x16x32_bf16 v[58:61], v[86:89], v[166:169], v[58:61]
	v_mfma_f32_16x16x32_bf16 v[46:49], v[70:73], v[174:177], v[46:49]
	v_mfma_f32_16x16x32_bf16 v[42:45], v[86:89], v[174:177], v[42:45]
	v_mfma_f32_16x16x32_bf16 v[30:33], v[70:73], v[182:185], v[30:33]
	v_mfma_f32_16x16x32_bf16 v[26:29], v[86:89], v[182:185], v[26:29]
	v_mfma_f32_16x16x32_bf16 v[14:17], v[70:73], v[220:223], v[14:17]
	v_mfma_f32_16x16x32_bf16 v[10:13], v[86:89], v[220:223], v[10:13]
	v_mfma_f32_16x16x32_bf16 v[54:57], v[146:149], v[162:165], v[54:57]
	v_mfma_f32_16x16x32_bf16 v[50:53], v[154:157], v[162:165], v[50:53]
	v_mfma_f32_16x16x32_bf16 v[38:41], v[146:149], v[170:173], v[38:41]
	v_mfma_f32_16x16x32_bf16 v[34:37], v[154:157], v[170:173], v[34:37]
	v_mfma_f32_16x16x32_bf16 v[22:25], v[146:149], v[178:181], v[22:25]
	v_mfma_f32_16x16x32_bf16 v[18:21], v[154:157], v[178:181], v[18:21]
	v_mfma_f32_16x16x32_bf16 v[6:9], v[146:149], v[216:219], v[6:9]
	v_mfma_f32_16x16x32_bf16 v[2:5], v[154:157], v[216:219], v[2:5]
	v_mfma_f32_16x16x32_bf16 v[54:57], v[150:153], v[166:169], v[54:57]
	v_mfma_f32_16x16x32_bf16 v[50:53], v[158:161], v[166:169], v[50:53]
	v_mfma_f32_16x16x32_bf16 v[38:41], v[150:153], v[174:177], v[38:41]
	v_mfma_f32_16x16x32_bf16 v[34:37], v[158:161], v[174:177], v[34:37]
	v_mfma_f32_16x16x32_bf16 v[22:25], v[150:153], v[182:185], v[22:25]
	v_mfma_f32_16x16x32_bf16 v[18:21], v[158:161], v[182:185], v[18:21]
	v_mfma_f32_16x16x32_bf16 v[6:9], v[150:153], v[220:223], v[6:9]
	v_mfma_f32_16x16x32_bf16 v[2:5], v[158:161], v[220:223], v[2:5]
	s_add_i32 s8, s8, 2
	s_add_u32 s38, s38, 0x100
	s_addc_u32 s39, s39, 0
	s_add_u32 s6, s6, 0x100
	s_addc_u32 s7, s7, 0
	s_cmp_gt_u32 s8, 29
	s_barrier
	s_cbranch_scc0 .LBB0_927
	s_and_b64 vcc, exec, s[70:71]
	s_cbranch_vccz .LBB0_930
	s_barrier

; #define PG8_STAGE(bufoff, gbase, voff) do { _Pragma("unroll") for (int _i = 0; _i < 2; ++_i) \
;         __builtin_amdgcn_global_load_lds((const unsigned*)((const char*)(gbase) + (voff)[_i]), (PG8_LAS unsigned*)(lds + (bufoff) + ldsw + _i * 8192), 16, 0, 0); } while (0)
; #define PG8_LDA(dst, b, h) do { _Pragma("unroll") for (int m = 0; m < 4; ++m) _Pragma("unroll") for (int k = 0; k < 2; ++k) dst[m][k] = *(const PG8_LAS bf16x8*)(lds + PG8_SA(b, h) + aoff + m * 2048 + k * 1024); } while (0)
; #define PG8_LDB(dst, b, h) do { _Pragma("unroll") for (int n = 0; n < 2; ++n) _Pragma("unroll") for (int k = 0; k < 2; ++k) dst[n][k] = *(const PG8_LAS bf16x8*)(lds + PG8_SB(b, h) + boff + n * 2048 + k * 1024); } while (0)
; #define PG8_MMA(ai, bj, At, Bt) do { __builtin_amdgcn_s_setprio(1); _Pragma("unroll") for (int m = 0; m < 4; ++m) _Pragma("unroll") for (int n = 0; n < 2; ++n) _Pragma("unroll") for (int k = 0; k < 2; ++k) \
;         acc[ai][bj][m][n] = __builtin_amdgcn_mfma_f32_16x16x32_bf16(Bt[n][k], At[m][k], acc[ai][bj][m][n], 0, 0, 0); __builtin_amdgcn_s_setprio(0); } while (0)
; #define PG8_BAR __builtin_amdgcn_s_barrier()
; template <class Epi, class Sched, bool ALIGN_EPI = false, bool SP2 = false>
; __device__ __forceinline__ void gemm_phase(PG8_LAS unsigned char* lds, const Gemm g, const Sched& S, const Epi& E) {
;     ...
;             const bool last = (t == nt - 2);
;             const char* a1 = cA + (size_t)(t + 1) * kstep;
;             const char* a2 = last ? nA : cA + (size_t)(t + 2) * kstep; const char* b2 = last ? nB : cB + (size_t)(t + 2) * kstep;
;             const char* a3 = a2 + kstep; const char* b3 = b2 + kstep;
;             if (last && has_next) S.a_ready(nxt);
;             if constexpr (SP2) {
;             PG8_LDB(B0, 0, 0); PG8_LDB(B1, 0, 1); PG8_SCHED; PG8_LDA(At, 0, 0); PG8_STAGE(PG8_SA(1, 1), a1 + hstep, voffA);
;             PG8_WAIT_V(8); PG8_WAIT_L(0); PG8_BAR; PG8_MMA(0, 0, At, B0); PG8_MMA(0, 1, At, B1); PG8_BAR; PG8_SCHED;
;             PG8_LDA(At, 0, 1); PG8_STAGE(PG8_SB(0, 0), b2, voffB); PG8_STAGE(PG8_SB(0, 1), b2 + hstepB, voffB); PG8_STAGE(PG8_SA(0, 0), a2, voffA);
;             PG8_WAIT_V(8); PG8_WAIT_L(0); PG8_BAR; PG8_MMA(1, 0, At, B0); PG8_MMA(1, 1, At, B1); PG8_BAR; PG8_SCHED;
;             PG8_LDB(B0, 1, 0); PG8_LDB(B1, 1, 1); PG8_SCHED; PG8_LDA(At, 1, 0); PG8_STAGE(PG8_SA(0, 1), a2 + hstep, voffA);
.LBB0_1071:
	s_add_u32 s10, s38, 0xffe00080
	s_addc_u32 s11, s39, -1
	s_add_i32 s12, 0, 0x10000
	s_cmpk_eq_i32 s9, 0x7c
	s_cselect_b32 vcc_hi, s97, s11
	s_cselect_b32 vcc_lo, s4, s10
	s_cselect_b32 s47, s5, s8
	s_cselect_b32 s46, s6, s7
	s_add_i32 s13, 0, 0x14000
	v_add_u32_e32 v152, s12, v164
	v_add_u32_e32 v167, s13, v164
	ds_read_b128 v[130:133], v152
	ds_read_b128 v[134:137], v152 offset:1024
	ds_read_b128 v[138:141], v152 offset:2048
	ds_read_b128 v[152:155], v152 offset:3072
	ds_read_b128 v[156:159], v167
	ds_read_b128 v[160:163], v167 offset:1024
	ds_read_b128 v[168:171], v167 offset:2048
	ds_read_b128 v[172:175], v167 offset:3072
	s_add_i32 m0, s74, 0xc000
	ds_read_b128 v[176:179], v166
	ds_read_b128 v[180:183], v166 offset:1024
	ds_read_b128 v[206:209], v166 offset:2048
	ds_read_b128 v[210:213], v166 offset:3072
	ds_read_b128 v[214:217], v166 offset:4096
	ds_read_b128 v[218:221], v166 offset:5120
	ds_read_b128 v[236:239], v166 offset:6144
	ds_read_b128 v[240:243], v166 offset:7168
	global_load_lds_dwordx4 v148, s[38:39]
	s_add_i32 m0, s74, 0xe000
	s_nop 0
	global_load_lds_dwordx4 v150, s[38:39]
	s_waitcnt vmcnt(8)
	s_waitcnt lgkmcnt(0)
	s_barrier
	v_mfma_f32_16x16x32_bf16 v[126:129], v[130:133], v[176:179], v[126:129]
	v_mfma_f32_16x16x32_bf16 v[122:125], v[138:141], v[176:179], v[122:125]
	v_mfma_f32_16x16x32_bf16 v[110:113], v[130:133], v[206:209], v[110:113]
	v_mfma_f32_16x16x32_bf16 v[106:109], v[138:141], v[206:209], v[106:109]
	v_mfma_f32_16x16x32_bf16 v[94:97], v[130:133], v[214:217], v[94:97]
	v_mfma_f32_16x16x32_bf16 v[90:93], v[138:141], v[214:217], v[90:93]
	v_mfma_f32_16x16x32_bf16 v[78:81], v[130:133], v[236:239], v[78:81]
	v_mfma_f32_16x16x32_bf16 v[74:77], v[138:141], v[236:239], v[74:77]
	v_mfma_f32_16x16x32_bf16 v[126:129], v[134:137], v[180:183], v[126:129]
	v_mfma_f32_16x16x32_bf16 v[122:125], v[152:155], v[180:183], v[122:125]
	v_mfma_f32_16x16x32_bf16 v[110:113], v[134:137], v[210:213], v[110:113]
	v_mfma_f32_16x16x32_bf16 v[106:109], v[152:155], v[210:213], v[106:109]
	v_mfma_f32_16x16x32_bf16 v[94:97], v[134:137], v[218:221], v[94:97]
	v_mfma_f32_16x16x32_bf16 v[90:93], v[152:155], v[218:221], v[90:93]
	v_mfma_f32_16x16x32_bf16 v[78:81], v[134:137], v[240:243], v[78:81]
	v_mfma_f32_16x16x32_bf16 v[74:77], v[152:155], v[240:243], v[74:77]
	v_mfma_f32_16x16x32_bf16 v[118:121], v[156:159], v[176:179], v[118:121]
	v_mfma_f32_16x16x32_bf16 v[114:117], v[168:171], v[176:179], v[114:117]
	v_mfma_f32_16x16x32_bf16 v[102:105], v[156:159], v[206:209], v[102:105]
	v_mfma_f32_16x16x32_bf16 v[98:101], v[168:171], v[206:209], v[98:101]
	v_mfma_f32_16x16x32_bf16 v[86:89], v[156:159], v[214:217], v[86:89]
	v_mfma_f32_16x16x32_bf16 v[82:85], v[168:171], v[214:217], v[82:85]
	v_mfma_f32_16x16x32_bf16 v[70:73], v[156:159], v[236:239], v[70:73]
	v_mfma_f32_16x16x32_bf16 v[66:69], v[168:171], v[236:239], v[66:69]
	v_mfma_f32_16x16x32_bf16 v[118:121], v[160:163], v[180:183], v[118:121]
	v_mfma_f32_16x16x32_bf16 v[114:117], v[172:175], v[180:183], v[114:117]
	v_mfma_f32_16x16x32_bf16 v[102:105], v[160:163], v[210:213], v[102:105]
	v_mfma_f32_16x16x32_bf16 v[98:101], v[172:175], v[210:213], v[98:101]
	v_mfma_f32_16x16x32_bf16 v[86:89], v[160:163], v[218:221], v[86:89]
	v_mfma_f32_16x16x32_bf16 v[82:85], v[172:175], v[218:221], v[82:85]
	v_mfma_f32_16x16x32_bf16 v[70:73], v[160:163], v[240:243], v[70:73]
	v_mfma_f32_16x16x32_bf16 v[66:69], v[172:175], v[240:243], v[66:69]
	s_add_i32 s10, s12, s67
	s_mov_b32 m0, s10
	s_barrier
	ds_read_b128 v[176:179], v166 offset:16384
	ds_read_b128 v[180:183], v166 offset:17408
	ds_read_b128 v[206:209], v166 offset:18432
	ds_read_b128 v[210:213], v166 offset:19456
	ds_read_b128 v[214:217], v166 offset:20480
	ds_read_b128 v[218:221], v166 offset:21504
	ds_read_b128 v[236:239], v166 offset:22528
	ds_read_b128 v[240:243], v166 offset:23552
	global_load_lds_dwordx4 v146, s[46:47]
	s_add_i32 m0, s10, 0x2000
	s_add_u32 s10, s46, 0x80000
	s_addc_u32 s11, s47, 0
	s_add_i32 s12, s13, s67
	global_load_lds_dwordx4 v142, s[46:47]
	s_mov_b32 m0, s12
	s_nop 0
	global_load_lds_dwordx4 v146, s[10:11]
	s_add_i32 m0, s12, 0x2000
	s_nop 0
	global_load_lds_dwordx4 v142, s[10:11]
	s_mov_b32 m0, s74
	s_nop 0
	global_load_lds_dwordx4 v190, vcc
	s_mov_b32 m0, s75
	s_nop 0
	global_load_lds_dwordx4 v144, vcc
	s_waitcnt vmcnt(8)
	s_waitcnt lgkmcnt(0)
	s_barrier
	v_mfma_f32_16x16x32_bf16 v[62:65], v[130:133], v[176:179], v[62:65]
	v_mfma_f32_16x16x32_bf16 v[58:61], v[138:141], v[176:179], v[58:61]
	v_mfma_f32_16x16x32_bf16 v[46:49], v[130:133], v[206:209], v[46:49]
	v_mfma_f32_16x16x32_bf16 v[42:45], v[138:141], v[206:209], v[42:45]
	v_mfma_f32_16x16x32_bf16 v[30:33], v[130:133], v[214:217], v[30:33]
	v_mfma_f32_16x16x32_bf16 v[26:29], v[138:141], v[214:217], v[26:29]
	v_mfma_f32_16x16x32_bf16 v[14:17], v[130:133], v[236:239], v[14:17]
	v_mfma_f32_16x16x32_bf16 v[10:13], v[138:141], v[236:239], v[10:13]
	v_mfma_f32_16x16x32_bf16 v[62:65], v[134:137], v[180:183], v[62:65]
	v_mfma_f32_16x16x32_bf16 v[58:61], v[152:155], v[180:183], v[58:61]
	v_mfma_f32_16x16x32_bf16 v[46:49], v[134:137], v[210:213], v[46:49]
	v_mfma_f32_16x16x32_bf16 v[42:45], v[152:155], v[210:213], v[42:45]
	v_mfma_f32_16x16x32_bf16 v[30:33], v[134:137], v[218:221], v[30:33]
	v_mfma_f32_16x16x32_bf16 v[26:29], v[152:155], v[218:221], v[26:29]
	v_mfma_f32_16x16x32_bf16 v[14:17], v[134:137], v[240:243], v[14:17]
	v_mfma_f32_16x16x32_bf16 v[10:13], v[152:155], v[240:243], v[10:13]
	v_mfma_f32_16x16x32_bf16 v[54:57], v[156:159], v[176:179], v[54:57]
	v_mfma_f32_16x16x32_bf16 v[50:53], v[168:171], v[176:179], v[50:53]
	v_mfma_f32_16x16x32_bf16 v[38:41], v[156:159], v[206:209], v[38:41]
	v_mfma_f32_16x16x32_bf16 v[34:37], v[168:171], v[206:209], v[34:37]
	v_mfma_f32_16x16x32_bf16 v[22:25], v[156:159], v[214:217], v[22:25]
	v_mfma_f32_16x16x32_bf16 v[18:21], v[168:171], v[214:217], v[18:21]
	v_mfma_f32_16x16x32_bf16 v[6:9], v[156:159], v[236:239], v[6:9]
	v_mfma_f32_16x16x32_bf16 v[2:5], v[168:171], v[236:239], v[2:5]
	v_mfma_f32_16x16x32_bf16 v[54:57], v[160:163], v[180:183], v[54:57]
	v_mfma_f32_16x16x32_bf16 v[50:53], v[172:175], v[180:183], v[50:53]
	v_mfma_f32_16x16x32_bf16 v[38:41], v[160:163], v[210:213], v[38:41]
	v_mfma_f32_16x16x32_bf16 v[34:37], v[172:175], v[210:213], v[34:37]
	v_mfma_f32_16x16x32_bf16 v[22:25], v[160:163], v[218:221], v[22:25]
	v_mfma_f32_16x16x32_bf16 v[18:21], v[172:175], v[218:221], v[18:21]
	v_mfma_f32_16x16x32_bf16 v[6:9], v[160:163], v[240:243], v[6:9]
	v_mfma_f32_16x16x32_bf16 v[2:5], v[172:175], v[240:243], v[2:5]
	s_add_i32 s12, 0, 0x18000
	s_add_i32 s13, 0, 0x1c000
	s_barrier
; #define PG8_STAGE(bufoff, gbase, voff) do { _Pragma("unroll") for (int _i = 0; _i < 2; ++_i) \
;         __builtin_amdgcn_global_load_lds((const unsigned*)((const char*)(gbase) + (voff)[_i]), (PG8_LAS unsigned*)(lds + (bufoff) + ldsw + _i * 8192), 16, 0, 0); } while (0)
; #define PG8_LDA(dst, b, h) do { _Pragma("unroll") for (int m = 0; m < 4; ++m) _Pragma("unroll") for (int k = 0; k < 2; ++k) dst[m][k] = *(const PG8_LAS bf16x8*)(lds + PG8_SA(b, h) + aoff + m * 2048 + k * 1024); } while (0)
; #define PG8_LDB(dst, b, h) do { _Pragma("unroll") for (int n = 0; n < 2; ++n) _Pragma("unroll") for (int k = 0; k < 2; ++k) dst[n][k] = *(const PG8_LAS bf16x8*)(lds + PG8_SB(b, h) + boff + n * 2048 + k * 1024); } while (0)
; #define PG8_MMA(ai, bj, At, Bt) do { __builtin_amdgcn_s_setprio(1); _Pragma("unroll") for (int m = 0; m < 4; ++m) _Pragma("unroll") for (int n = 0; n < 2; ++n) _Pragma("unroll") for (int k = 0; k < 2; ++k) \
;         acc[ai][bj][m][n] = __builtin_amdgcn_mfma_f32_16x16x32_bf16(Bt[n][k], At[m][k], acc[ai][bj][m][n], 0, 0, 0); __builtin_amdgcn_s_setprio(0); } while (0)
; #define PG8_WAIT_V(n) asm volatile("s_waitcnt vmcnt(" #n ")" ::: "memory")
; #define PG8_WAIT_L(n) asm volatile("s_waitcnt lgkmcnt(" #n ")" ::: "memory")
; #define PG8_BAR __builtin_amdgcn_s_barrier()
; #define PG8_SCHED __builtin_amdgcn_sched_barrier(0)
; template <class Epi, class Sched, bool ALIGN_EPI = false, bool SP2 = false>
; __device__ __forceinline__ void gemm_phase(PG8_LAS unsigned char* lds, const Gemm g, const Sched& S, const Epi& E) {
;     ...
;             PG8_LDB(B0, 1, 0); PG8_LDB(B1, 1, 1); PG8_SCHED; PG8_LDA(At, 1, 0); PG8_STAGE(PG8_SA(0, 1), a2 + hstep, voffA);
;             PG8_WAIT_V(8); PG8_WAIT_L(0); PG8_BAR; PG8_MMA(0, 0, At, B0); PG8_MMA(0, 1, At, B1); PG8_BAR; PG8_SCHED;
;             PG8_LDA(At, 1, 1); PG8_STAGE(PG8_SB(1, 0), b3, voffB); PG8_STAGE(PG8_SB(1, 1), b3 + hstepB, voffB); PG8_STAGE(PG8_SA(1, 0), a3, voffA);
;             PG8_WAIT_V(8); PG8_WAIT_L(0); PG8_BAR; PG8_MMA(1, 0, At, B0); PG8_MMA(1, 1, At, B1); PG8_BAR; PG8_SCHED;
	v_add_u32_e32 v152, s12, v164
	v_add_u32_e32 v167, s13, v164
	ds_read_b128 v[130:133], v152
	ds_read_b128 v[134:137], v152 offset:1024
	ds_read_b128 v[138:141], v152 offset:2048
	ds_read_b128 v[152:155], v152 offset:3072
	ds_read_b128 v[156:159], v167
	ds_read_b128 v[160:163], v167 offset:1024
	ds_read_b128 v[168:171], v167 offset:2048
	ds_read_b128 v[172:175], v167 offset:3072
	s_add_u32 s10, vcc_lo, 0x200000
	s_addc_u32 s11, vcc_hi, 0
	s_mov_b32 m0, s86
	ds_read_b128 v[176:179], v166 offset:32768
	ds_read_b128 v[180:183], v166 offset:33792
	ds_read_b128 v[206:209], v166 offset:34816
	ds_read_b128 v[210:213], v166 offset:35840
	ds_read_b128 v[214:217], v166 offset:36864
	ds_read_b128 v[218:221], v166 offset:37888
	ds_read_b128 v[236:239], v166 offset:38912
	ds_read_b128 v[240:243], v166 offset:39936
	global_load_lds_dwordx4 v190, s[10:11]
	s_mov_b32 m0, s87
	s_nop 0
	global_load_lds_dwordx4 v144, s[10:11]
	s_waitcnt vmcnt(8)
	s_waitcnt lgkmcnt(0)
	s_barrier
	v_mfma_f32_16x16x32_bf16 v[126:129], v[130:133], v[176:179], v[126:129]
	v_mfma_f32_16x16x32_bf16 v[122:125], v[138:141], v[176:179], v[122:125]
	v_mfma_f32_16x16x32_bf16 v[110:113], v[130:133], v[206:209], v[110:113]
	v_mfma_f32_16x16x32_bf16 v[106:109], v[138:141], v[206:209], v[106:109]
	v_mfma_f32_16x16x32_bf16 v[94:97], v[130:133], v[214:217], v[94:97]
	v_mfma_f32_16x16x32_bf16 v[90:93], v[138:141], v[214:217], v[90:93]
	v_mfma_f32_16x16x32_bf16 v[78:81], v[130:133], v[236:239], v[78:81]
	v_mfma_f32_16x16x32_bf16 v[74:77], v[138:141], v[236:239], v[74:77]
	v_mfma_f32_16x16x32_bf16 v[126:129], v[134:137], v[180:183], v[126:129]
	v_mfma_f32_16x16x32_bf16 v[122:125], v[152:155], v[180:183], v[122:125]
	v_mfma_f32_16x16x32_bf16 v[110:113], v[134:137], v[210:213], v[110:113]
	v_mfma_f32_16x16x32_bf16 v[106:109], v[152:155], v[210:213], v[106:109]
	v_mfma_f32_16x16x32_bf16 v[94:97], v[134:137], v[218:221], v[94:97]
	v_mfma_f32_16x16x32_bf16 v[90:93], v[152:155], v[218:221], v[90:93]
	v_mfma_f32_16x16x32_bf16 v[78:81], v[134:137], v[240:243], v[78:81]
	v_mfma_f32_16x16x32_bf16 v[74:77], v[152:155], v[240:243], v[74:77]
	v_mfma_f32_16x16x32_bf16 v[118:121], v[156:159], v[176:179], v[118:121]
	v_mfma_f32_16x16x32_bf16 v[114:117], v[168:171], v[176:179], v[114:117]
	v_mfma_f32_16x16x32_bf16 v[102:105], v[156:159], v[206:209], v[102:105]
	v_mfma_f32_16x16x32_bf16 v[98:101], v[168:171], v[206:209], v[98:101]
	v_mfma_f32_16x16x32_bf16 v[86:89], v[156:159], v[214:217], v[86:89]
	v_mfma_f32_16x16x32_bf16 v[82:85], v[168:171], v[214:217], v[82:85]
	v_mfma_f32_16x16x32_bf16 v[70:73], v[156:159], v[236:239], v[70:73]
	v_mfma_f32_16x16x32_bf16 v[66:69], v[168:171], v[236:239], v[66:69]
	v_mfma_f32_16x16x32_bf16 v[118:121], v[160:163], v[180:183], v[118:121]
	v_mfma_f32_16x16x32_bf16 v[114:117], v[172:175], v[180:183], v[114:117]
	v_mfma_f32_16x16x32_bf16 v[102:105], v[160:163], v[210:213], v[102:105]
	v_mfma_f32_16x16x32_bf16 v[98:101], v[172:175], v[210:213], v[98:101]
	v_mfma_f32_16x16x32_bf16 v[86:89], v[160:163], v[218:221], v[86:89]
	v_mfma_f32_16x16x32_bf16 v[82:85], v[172:175], v[218:221], v[82:85]
	v_mfma_f32_16x16x32_bf16 v[70:73], v[160:163], v[240:243], v[70:73]
	v_mfma_f32_16x16x32_bf16 v[66:69], v[172:175], v[240:243], v[66:69]
	s_add_i32 s10, s12, s67
	s_mov_b32 m0, s10
	s_barrier
	ds_read_b128 v[176:179], v166 offset:49152
	ds_read_b128 v[180:183], v166 offset:50176
	ds_read_b128 v[206:209], v166 offset:51200
	ds_read_b128 v[210:213], v166 offset:52224
	ds_read_b128 v[214:217], v166 offset:53248
	ds_read_b128 v[218:221], v166 offset:54272
	ds_read_b128 v[236:239], v166 offset:55296
	ds_read_b128 v[240:243], v166 offset:56320
	s_add_u32 s100, s46, s60
	s_addc_u32 s101, s47, s61
	global_load_lds_dwordx4 v146, s[100:101]
	s_add_i32 m0, s10, 0x2000
	s_add_u32 s10, s46, 0x80080
	s_addc_u32 s11, s47, 0
	s_add_i32 s12, s13, s67
	global_load_lds_dwordx4 v142, s[100:101]
	s_mov_b32 m0, s12
	s_nop 0
	global_load_lds_dwordx4 v146, s[10:11]
	s_add_i32 m0, s12, 0x2000
	s_nop 0
	global_load_lds_dwordx4 v142, s[10:11]
	s_mov_b32 m0, s82
	s_add_u32 s100, vcc_lo, s60
	s_addc_u32 s101, vcc_hi, s61
	global_load_lds_dwordx4 v190, s[100:101]
	s_mov_b32 m0, s42
	s_nop 0
	global_load_lds_dwordx4 v144, s[100:101]
	s_waitcnt vmcnt(8)
	s_waitcnt lgkmcnt(0)
	s_barrier
	v_mfma_f32_16x16x32_bf16 v[62:65], v[130:133], v[176:179], v[62:65]
	v_mfma_f32_16x16x32_bf16 v[58:61], v[138:141], v[176:179], v[58:61]
	v_mfma_f32_16x16x32_bf16 v[46:49], v[130:133], v[206:209], v[46:49]
	v_mfma_f32_16x16x32_bf16 v[42:45], v[138:141], v[206:209], v[42:45]
	v_mfma_f32_16x16x32_bf16 v[30:33], v[130:133], v[214:217], v[30:33]
	v_mfma_f32_16x16x32_bf16 v[26:29], v[138:141], v[214:217], v[26:29]
	v_mfma_f32_16x16x32_bf16 v[14:17], v[130:133], v[236:239], v[14:17]
	v_mfma_f32_16x16x32_bf16 v[10:13], v[138:141], v[236:239], v[10:13]
	v_mfma_f32_16x16x32_bf16 v[62:65], v[134:137], v[180:183], v[62:65]
	v_mfma_f32_16x16x32_bf16 v[58:61], v[152:155], v[180:183], v[58:61]
	v_mfma_f32_16x16x32_bf16 v[46:49], v[134:137], v[210:213], v[46:49]
	v_mfma_f32_16x16x32_bf16 v[42:45], v[152:155], v[210:213], v[42:45]
	v_mfma_f32_16x16x32_bf16 v[30:33], v[134:137], v[218:221], v[30:33]
	v_mfma_f32_16x16x32_bf16 v[26:29], v[152:155], v[218:221], v[26:29]
	v_mfma_f32_16x16x32_bf16 v[14:17], v[134:137], v[240:243], v[14:17]
	v_mfma_f32_16x16x32_bf16 v[10:13], v[152:155], v[240:243], v[10:13]
	v_mfma_f32_16x16x32_bf16 v[54:57], v[156:159], v[176:179], v[54:57]
	v_mfma_f32_16x16x32_bf16 v[50:53], v[168:171], v[176:179], v[50:53]
	v_mfma_f32_16x16x32_bf16 v[38:41], v[156:159], v[206:209], v[38:41]
	v_mfma_f32_16x16x32_bf16 v[34:37], v[168:171], v[206:209], v[34:37]
	v_mfma_f32_16x16x32_bf16 v[22:25], v[156:159], v[214:217], v[22:25]
	v_mfma_f32_16x16x32_bf16 v[18:21], v[168:171], v[214:217], v[18:21]
	v_mfma_f32_16x16x32_bf16 v[6:9], v[156:159], v[236:239], v[6:9]
	v_mfma_f32_16x16x32_bf16 v[2:5], v[168:171], v[236:239], v[2:5]
	v_mfma_f32_16x16x32_bf16 v[54:57], v[160:163], v[180:183], v[54:57]
	v_mfma_f32_16x16x32_bf16 v[50:53], v[172:175], v[180:183], v[50:53]
	v_mfma_f32_16x16x32_bf16 v[38:41], v[160:163], v[210:213], v[38:41]
	v_mfma_f32_16x16x32_bf16 v[34:37], v[172:175], v[210:213], v[34:37]
	v_mfma_f32_16x16x32_bf16 v[22:25], v[160:163], v[218:221], v[22:25]
	v_mfma_f32_16x16x32_bf16 v[18:21], v[172:175], v[218:221], v[18:21]
	v_mfma_f32_16x16x32_bf16 v[6:9], v[160:163], v[240:243], v[6:9]
	v_mfma_f32_16x16x32_bf16 v[2:5], v[172:175], v[240:243], v[2:5]
	s_add_i32 s9, s9, 2
	s_add_u32 s38, s38, 0x100
	s_addc_u32 s39, s39, 0
	s_add_u32 s7, s7, 0x100
	s_addc_u32 s8, s8, 0
	s_cmpk_gt_u32 s9, 0x7d
	s_barrier
	s_cbranch_scc0 .LBB0_1071
	s_and_b64 vcc, exec, s[72:73]
	s_cbranch_vccz .LBB0_1074
	s_barrier

; #define PG8_STAGE(bufoff, gbase, voff) do { _Pragma("unroll") for (int _i = 0; _i < 2; ++_i) \
;         __builtin_amdgcn_global_load_lds((const unsigned*)((const char*)(gbase) + (voff)[_i]), (PG8_LAS unsigned*)(lds + (bufoff) + ldsw + _i * 8192), 16, 0, 0); } while (0)
; #define PG8_LDA(dst, b, h) do { _Pragma("unroll") for (int m = 0; m < 4; ++m) _Pragma("unroll") for (int k = 0; k < 2; ++k) dst[m][k] = *(const PG8_LAS bf16x8*)(lds + PG8_SA(b, h) + aoff + m * 2048 + k * 1024); } while (0)
; #define PG8_LDB(dst, b, h) do { _Pragma("unroll") for (int n = 0; n < 2; ++n) _Pragma("unroll") for (int k = 0; k < 2; ++k) dst[n][k] = *(const PG8_LAS bf16x8*)(lds + PG8_SB(b, h) + boff + n * 2048 + k * 1024); } while (0)
; #define PG8_MMA(ai, bj, At, Bt) do { __builtin_amdgcn_s_setprio(1); _Pragma("unroll") for (int m = 0; m < 4; ++m) _Pragma("unroll") for (int n = 0; n < 2; ++n) _Pragma("unroll") for (int k = 0; k < 2; ++k) \
;         acc[ai][bj][m][n] = __builtin_amdgcn_mfma_f32_16x16x32_bf16(Bt[n][k], At[m][k], acc[ai][bj][m][n], 0, 0, 0); __builtin_amdgcn_s_setprio(0); } while (0)
; #define PG8_BAR __builtin_amdgcn_s_barrier()
; template <class Epi, class Sched, bool ALIGN_EPI = false, bool SP2 = false>
; __device__ __forceinline__ void gemm_phase(PG8_LAS unsigned char* lds, const Gemm g, const Sched& S, const Epi& E) {
;     ...
;             const bool last = (t == nt - 2);
;             const char* a1 = cA + (size_t)(t + 1) * kstep;
;             const char* a2 = last ? nA : cA + (size_t)(t + 2) * kstep; const char* b2 = last ? nB : cB + (size_t)(t + 2) * kstep;
;             const char* a3 = a2 + kstep; const char* b3 = b2 + kstep;
;             if (last && has_next) S.a_ready(nxt);
;             if constexpr (SP2) {
;             PG8_LDB(B0, 0, 0); PG8_LDB(B1, 0, 1); PG8_SCHED; PG8_LDA(At, 0, 0); PG8_STAGE(PG8_SA(1, 1), a1 + hstep, voffA);
;             PG8_WAIT_V(8); PG8_WAIT_L(0); PG8_BAR; PG8_MMA(0, 0, At, B0); PG8_MMA(0, 1, At, B1); PG8_BAR; PG8_SCHED;
;             PG8_LDA(At, 0, 1); PG8_STAGE(PG8_SB(0, 0), b2, voffB); PG8_STAGE(PG8_SB(0, 1), b2 + hstepB, voffB); PG8_STAGE(PG8_SA(0, 0), a2, voffA);
;             PG8_WAIT_V(8); PG8_WAIT_L(0); PG8_BAR; PG8_MMA(1, 0, At, B0); PG8_MMA(1, 1, At, B1); PG8_BAR; PG8_SCHED;
;             PG8_LDB(B0, 1, 0); PG8_LDB(B1, 1, 1); PG8_SCHED; PG8_LDA(At, 1, 0); PG8_STAGE(PG8_SA(0, 1), a2 + hstep, voffA);
.LBB0_1233:
	s_add_u32 s9, s68, s80
	s_addc_u32 s10, s69, s81
	s_add_u32 s9, s9, 0x100
	s_addc_u32 s10, s10, 0
	s_add_u32 s100, s9, 0x7ff80
	s_addc_u32 s101, s10, 0
	s_add_u32 s11, s36, s80
	s_addc_u32 s12, s37, s81
	s_add_i32 s13, 0, 0x10000
	s_cmpk_eq_i32 s80, 0xf00
	s_cselect_b32 s93, s4, s10
	s_cselect_b32 s92, s5, s9
	v_add_u32_e32 v144, s13, v145
	s_cselect_b32 s85, s6, s12
	s_cselect_b32 s84, s7, s11
	s_add_i32 s9, 0, 0x14000
	ds_read_b128 v[152:155], v144
	ds_read_b128 v[156:159], v144 offset:1024
	ds_read_b128 v[160:163], v144 offset:2048
	ds_read_b128 v[164:167], v144 offset:3072
	v_add_u32_e32 v144, s9, v145
	ds_read_b128 v[168:171], v144
	ds_read_b128 v[172:175], v144 offset:1024
	ds_read_b128 v[176:179], v144 offset:2048
	ds_read_b128 v[180:183], v144 offset:3072
	s_add_i32 m0, s51, 0xc000
	ds_read_b128 v[206:209], v151
	ds_read_b128 v[210:213], v151 offset:1024
	ds_read_b128 v[214:217], v151 offset:2048
	ds_read_b128 v[218:221], v151 offset:3072
	ds_read_b128 v[236:239], v151 offset:4096
	ds_read_b128 v[240:243], v151 offset:5120
	ds_read_b128 v[244:247], v151 offset:6144
	ds_read_b128 v[194:197], v151 offset:7168
	global_load_lds_dwordx4 v136, s[100:101]
	s_add_i32 m0, s51, 0xe000
	s_nop 0
	global_load_lds_dwordx4 v138, s[100:101]
	s_waitcnt vmcnt(8)
	s_waitcnt lgkmcnt(0)
	s_barrier
	v_mfma_f32_16x16x32_bf16 v[126:129], v[152:155], v[206:209], v[126:129]
	v_mfma_f32_16x16x32_bf16 v[122:125], v[160:163], v[206:209], v[122:125]
	v_mfma_f32_16x16x32_bf16 v[118:121], v[152:155], v[214:217], v[118:121]
	v_mfma_f32_16x16x32_bf16 v[114:117], v[160:163], v[214:217], v[114:117]
	v_mfma_f32_16x16x32_bf16 v[110:113], v[152:155], v[236:239], v[110:113]
	v_mfma_f32_16x16x32_bf16 v[106:109], v[160:163], v[236:239], v[106:109]
	v_mfma_f32_16x16x32_bf16 v[102:105], v[152:155], v[244:247], v[102:105]
	v_mfma_f32_16x16x32_bf16 v[98:101], v[160:163], v[244:247], v[98:101]
	v_mfma_f32_16x16x32_bf16 v[126:129], v[156:159], v[210:213], v[126:129]
	v_mfma_f32_16x16x32_bf16 v[122:125], v[164:167], v[210:213], v[122:125]
	v_mfma_f32_16x16x32_bf16 v[118:121], v[156:159], v[218:221], v[118:121]
	v_mfma_f32_16x16x32_bf16 v[114:117], v[164:167], v[218:221], v[114:117]
	v_mfma_f32_16x16x32_bf16 v[110:113], v[156:159], v[240:243], v[110:113]
	v_mfma_f32_16x16x32_bf16 v[106:109], v[164:167], v[240:243], v[106:109]
	v_mfma_f32_16x16x32_bf16 v[102:105], v[156:159], v[194:197], v[102:105]
	v_mfma_f32_16x16x32_bf16 v[98:101], v[164:167], v[194:197], v[98:101]
	v_mfma_f32_16x16x32_bf16 v[94:97], v[168:171], v[206:209], v[94:97]
	v_mfma_f32_16x16x32_bf16 v[90:93], v[176:179], v[206:209], v[90:93]
	v_mfma_f32_16x16x32_bf16 v[86:89], v[168:171], v[214:217], v[86:89]
	v_mfma_f32_16x16x32_bf16 v[82:85], v[176:179], v[214:217], v[82:85]
	v_mfma_f32_16x16x32_bf16 v[78:81], v[168:171], v[236:239], v[78:81]
	v_mfma_f32_16x16x32_bf16 v[74:77], v[176:179], v[236:239], v[74:77]
	v_mfma_f32_16x16x32_bf16 v[70:73], v[168:171], v[244:247], v[70:73]
	v_mfma_f32_16x16x32_bf16 v[66:69], v[176:179], v[244:247], v[66:69]
	v_mfma_f32_16x16x32_bf16 v[94:97], v[172:175], v[210:213], v[94:97]
	v_mfma_f32_16x16x32_bf16 v[90:93], v[180:183], v[210:213], v[90:93]
	v_mfma_f32_16x16x32_bf16 v[86:89], v[172:175], v[218:221], v[86:89]
	v_mfma_f32_16x16x32_bf16 v[82:85], v[180:183], v[218:221], v[82:85]
	v_mfma_f32_16x16x32_bf16 v[78:81], v[172:175], v[240:243], v[78:81]
	v_mfma_f32_16x16x32_bf16 v[74:77], v[180:183], v[240:243], v[74:77]
	v_mfma_f32_16x16x32_bf16 v[70:73], v[172:175], v[194:197], v[70:73]
	v_mfma_f32_16x16x32_bf16 v[66:69], v[180:183], v[194:197], v[66:69]
	s_add_i32 s10, s13, s42
	s_mov_b32 m0, s10
	s_barrier
	ds_read_b128 v[194:197], v151 offset:16384
	ds_read_b128 v[206:209], v151 offset:17408
	ds_read_b128 v[210:213], v151 offset:18432
	ds_read_b128 v[214:217], v151 offset:19456
	ds_read_b128 v[218:221], v151 offset:20480
	ds_read_b128 v[236:239], v151 offset:21504
	ds_read_b128 v[240:243], v151 offset:22528
	ds_read_b128 v[244:247], v151 offset:23552
	global_load_lds_dwordx4 v130, s[84:85]
	s_add_i32 m0, s10, 0x2000
	s_add_u32 s10, s84, 0x20000
	s_addc_u32 s11, s85, 0
	s_add_i32 s9, s9, s42
	global_load_lds_dwordx4 v134, s[84:85]
	s_mov_b32 m0, s9
	s_nop 0
	global_load_lds_dwordx4 v130, s[10:11]
	s_add_i32 m0, s9, 0x2000
	s_nop 0
	global_load_lds_dwordx4 v134, s[10:11]
	s_mov_b32 m0, s51
	s_nop 0
	global_load_lds_dwordx4 v190, s[92:93]
	s_mov_b32 m0, s67
	s_nop 0
	global_load_lds_dwordx4 v132, s[92:93]
	s_waitcnt vmcnt(8)
	s_waitcnt lgkmcnt(0)
	s_barrier
	v_mfma_f32_16x16x32_bf16 v[62:65], v[152:155], v[194:197], v[62:65]
	v_mfma_f32_16x16x32_bf16 v[58:61], v[160:163], v[194:197], v[58:61]
	v_mfma_f32_16x16x32_bf16 v[54:57], v[152:155], v[210:213], v[54:57]
	v_mfma_f32_16x16x32_bf16 v[50:53], v[160:163], v[210:213], v[50:53]
	v_mfma_f32_16x16x32_bf16 v[46:49], v[152:155], v[218:221], v[46:49]
	v_mfma_f32_16x16x32_bf16 v[42:45], v[160:163], v[218:221], v[42:45]
	v_mfma_f32_16x16x32_bf16 v[38:41], v[152:155], v[240:243], v[38:41]
	v_mfma_f32_16x16x32_bf16 v[34:37], v[160:163], v[240:243], v[34:37]
	v_mfma_f32_16x16x32_bf16 v[62:65], v[156:159], v[206:209], v[62:65]
	v_mfma_f32_16x16x32_bf16 v[58:61], v[164:167], v[206:209], v[58:61]
	v_mfma_f32_16x16x32_bf16 v[54:57], v[156:159], v[214:217], v[54:57]
	v_mfma_f32_16x16x32_bf16 v[50:53], v[164:167], v[214:217], v[50:53]
	v_mfma_f32_16x16x32_bf16 v[46:49], v[156:159], v[236:239], v[46:49]
	v_mfma_f32_16x16x32_bf16 v[42:45], v[164:167], v[236:239], v[42:45]
	v_mfma_f32_16x16x32_bf16 v[38:41], v[156:159], v[244:247], v[38:41]
	v_mfma_f32_16x16x32_bf16 v[34:37], v[164:167], v[244:247], v[34:37]
	v_mfma_f32_16x16x32_bf16 v[30:33], v[168:171], v[194:197], v[30:33]
	v_mfma_f32_16x16x32_bf16 v[26:29], v[176:179], v[194:197], v[26:29]
	v_mfma_f32_16x16x32_bf16 v[22:25], v[168:171], v[210:213], v[22:25]
	v_mfma_f32_16x16x32_bf16 v[18:21], v[176:179], v[210:213], v[18:21]
	v_mfma_f32_16x16x32_bf16 v[14:17], v[168:171], v[218:221], v[14:17]
	v_mfma_f32_16x16x32_bf16 v[10:13], v[176:179], v[218:221], v[10:13]
	v_mfma_f32_16x16x32_bf16 v[6:9], v[168:171], v[240:243], v[6:9]
	v_mfma_f32_16x16x32_bf16 v[2:5], v[176:179], v[240:243], v[2:5]
	v_mfma_f32_16x16x32_bf16 v[30:33], v[172:175], v[206:209], v[30:33]
	v_mfma_f32_16x16x32_bf16 v[26:29], v[180:183], v[206:209], v[26:29]
	v_mfma_f32_16x16x32_bf16 v[22:25], v[172:175], v[214:217], v[22:25]
	v_mfma_f32_16x16x32_bf16 v[18:21], v[180:183], v[214:217], v[18:21]
	v_mfma_f32_16x16x32_bf16 v[14:17], v[172:175], v[236:239], v[14:17]
	v_mfma_f32_16x16x32_bf16 v[10:13], v[180:183], v[236:239], v[10:13]
	v_mfma_f32_16x16x32_bf16 v[6:9], v[172:175], v[244:247], v[6:9]
	v_mfma_f32_16x16x32_bf16 v[2:5], v[180:183], v[244:247], v[2:5]
	s_add_i32 s9, 0, 0x18000
	s_barrier
; #define PG8_STAGE(bufoff, gbase, voff) do { _Pragma("unroll") for (int _i = 0; _i < 2; ++_i) \
;         __builtin_amdgcn_global_load_lds((const unsigned*)((const char*)(gbase) + (voff)[_i]), (PG8_LAS unsigned*)(lds + (bufoff) + ldsw + _i * 8192), 16, 0, 0); } while (0)
; #define PG8_LDA(dst, b, h) do { _Pragma("unroll") for (int m = 0; m < 4; ++m) _Pragma("unroll") for (int k = 0; k < 2; ++k) dst[m][k] = *(const PG8_LAS bf16x8*)(lds + PG8_SA(b, h) + aoff + m * 2048 + k * 1024); } while (0)
; #define PG8_LDB(dst, b, h) do { _Pragma("unroll") for (int n = 0; n < 2; ++n) _Pragma("unroll") for (int k = 0; k < 2; ++k) dst[n][k] = *(const PG8_LAS bf16x8*)(lds + PG8_SB(b, h) + boff + n * 2048 + k * 1024); } while (0)
; #define PG8_MMA(ai, bj, At, Bt) do { __builtin_amdgcn_s_setprio(1); _Pragma("unroll") for (int m = 0; m < 4; ++m) _Pragma("unroll") for (int n = 0; n < 2; ++n) _Pragma("unroll") for (int k = 0; k < 2; ++k) \
;         acc[ai][bj][m][n] = __builtin_amdgcn_mfma_f32_16x16x32_bf16(Bt[n][k], At[m][k], acc[ai][bj][m][n], 0, 0, 0); __builtin_amdgcn_s_setprio(0); } while (0)
; #define PG8_WAIT_V(n) asm volatile("s_waitcnt vmcnt(" #n ")" ::: "memory")
; #define PG8_WAIT_L(n) asm volatile("s_waitcnt lgkmcnt(" #n ")" ::: "memory")
; #define PG8_BAR __builtin_amdgcn_s_barrier()
; #define PG8_SCHED __builtin_amdgcn_sched_barrier(0)
; template <class Epi, class Sched, bool ALIGN_EPI = false, bool SP2 = false>
; __device__ __forceinline__ void gemm_phase(PG8_LAS unsigned char* lds, const Gemm g, const Sched& S, const Epi& E) {
;     ...
;             PG8_LDB(B0, 1, 0); PG8_LDB(B1, 1, 1); PG8_SCHED; PG8_LDA(At, 1, 0); PG8_STAGE(PG8_SA(0, 1), a2 + hstep, voffA);
;             PG8_WAIT_V(8); PG8_WAIT_L(0); PG8_BAR; PG8_MMA(0, 0, At, B0); PG8_MMA(0, 1, At, B1); PG8_BAR; PG8_SCHED;
;             PG8_LDA(At, 1, 1); PG8_STAGE(PG8_SB(1, 0), b3, voffB); PG8_STAGE(PG8_SB(1, 1), b3 + hstepB, voffB); PG8_STAGE(PG8_SA(1, 0), a3, voffA);
;             PG8_WAIT_V(8); PG8_WAIT_L(0); PG8_BAR; PG8_MMA(1, 0, At, B0); PG8_MMA(1, 1, At, B1); PG8_BAR; PG8_SCHED;
	v_add_u32_e32 v144, s9, v145
	s_add_i32 s12, 0, 0x1c000
	ds_read_b128 v[152:155], v144
	ds_read_b128 v[156:159], v144 offset:1024
	ds_read_b128 v[160:163], v144 offset:2048
	ds_read_b128 v[164:167], v144 offset:3072
	v_add_u32_e32 v144, s12, v145
	ds_read_b128 v[168:171], v144
	ds_read_b128 v[172:175], v144 offset:1024
	ds_read_b128 v[176:179], v144 offset:2048
	ds_read_b128 v[180:183], v144 offset:3072
	s_add_u32 s10, s92, 0x80000
	s_addc_u32 s11, s93, 0
	s_mov_b32 m0, s74
	ds_read_b128 v[194:197], v151 offset:32768
	ds_read_b128 v[206:209], v151 offset:33792
	ds_read_b128 v[210:213], v151 offset:34816
	ds_read_b128 v[214:217], v151 offset:35840
	ds_read_b128 v[218:221], v151 offset:36864
	ds_read_b128 v[236:239], v151 offset:37888
	ds_read_b128 v[240:243], v151 offset:38912
	ds_read_b128 v[244:247], v151 offset:39936
	global_load_lds_dwordx4 v190, s[10:11]
	s_mov_b32 m0, s75
	s_nop 0
	global_load_lds_dwordx4 v132, s[10:11]
	s_waitcnt vmcnt(8)
	s_waitcnt lgkmcnt(0)
	s_barrier
	v_mfma_f32_16x16x32_bf16 v[126:129], v[152:155], v[194:197], v[126:129]
	v_mfma_f32_16x16x32_bf16 v[122:125], v[160:163], v[194:197], v[122:125]
	v_mfma_f32_16x16x32_bf16 v[118:121], v[152:155], v[210:213], v[118:121]
	v_mfma_f32_16x16x32_bf16 v[114:117], v[160:163], v[210:213], v[114:117]
	v_mfma_f32_16x16x32_bf16 v[110:113], v[152:155], v[218:221], v[110:113]
	v_mfma_f32_16x16x32_bf16 v[106:109], v[160:163], v[218:221], v[106:109]
	v_mfma_f32_16x16x32_bf16 v[102:105], v[152:155], v[240:243], v[102:105]
	v_mfma_f32_16x16x32_bf16 v[98:101], v[160:163], v[240:243], v[98:101]
	v_mfma_f32_16x16x32_bf16 v[126:129], v[156:159], v[206:209], v[126:129]
	v_mfma_f32_16x16x32_bf16 v[122:125], v[164:167], v[206:209], v[122:125]
	v_mfma_f32_16x16x32_bf16 v[118:121], v[156:159], v[214:217], v[118:121]
	v_mfma_f32_16x16x32_bf16 v[114:117], v[164:167], v[214:217], v[114:117]
	v_mfma_f32_16x16x32_bf16 v[110:113], v[156:159], v[236:239], v[110:113]
	v_mfma_f32_16x16x32_bf16 v[106:109], v[164:167], v[236:239], v[106:109]
	v_mfma_f32_16x16x32_bf16 v[102:105], v[156:159], v[244:247], v[102:105]
	v_mfma_f32_16x16x32_bf16 v[98:101], v[164:167], v[244:247], v[98:101]
	v_mfma_f32_16x16x32_bf16 v[94:97], v[168:171], v[194:197], v[94:97]
	v_mfma_f32_16x16x32_bf16 v[90:93], v[176:179], v[194:197], v[90:93]
	v_mfma_f32_16x16x32_bf16 v[86:89], v[168:171], v[210:213], v[86:89]
	v_mfma_f32_16x16x32_bf16 v[82:85], v[176:179], v[210:213], v[82:85]
	v_mfma_f32_16x16x32_bf16 v[78:81], v[168:171], v[218:221], v[78:81]
	v_mfma_f32_16x16x32_bf16 v[74:77], v[176:179], v[218:221], v[74:77]
	v_mfma_f32_16x16x32_bf16 v[70:73], v[168:171], v[240:243], v[70:73]
	v_mfma_f32_16x16x32_bf16 v[66:69], v[176:179], v[240:243], v[66:69]
	v_mfma_f32_16x16x32_bf16 v[94:97], v[172:175], v[206:209], v[94:97]
	v_mfma_f32_16x16x32_bf16 v[90:93], v[180:183], v[206:209], v[90:93]
	v_mfma_f32_16x16x32_bf16 v[86:89], v[172:175], v[214:217], v[86:89]
	v_mfma_f32_16x16x32_bf16 v[82:85], v[180:183], v[214:217], v[82:85]
	v_mfma_f32_16x16x32_bf16 v[78:81], v[172:175], v[236:239], v[78:81]
	v_mfma_f32_16x16x32_bf16 v[74:77], v[180:183], v[236:239], v[74:77]
	v_mfma_f32_16x16x32_bf16 v[70:73], v[172:175], v[244:247], v[70:73]
	v_mfma_f32_16x16x32_bf16 v[66:69], v[180:183], v[244:247], v[66:69]
	s_add_i32 s9, s9, s42
	s_mov_b32 m0, s9
	s_barrier
	ds_read_b128 v[194:197], v151 offset:49152
	ds_read_b128 v[206:209], v151 offset:50176
	ds_read_b128 v[210:213], v151 offset:51200
	ds_read_b128 v[214:217], v151 offset:52224
	ds_read_b128 v[218:221], v151 offset:53248
	ds_read_b128 v[236:239], v151 offset:54272
	ds_read_b128 v[240:243], v151 offset:55296
	ds_read_b128 v[244:247], v151 offset:56320
	s_add_u32 s100, s84, s60
	s_addc_u32 s101, s85, s61
	global_load_lds_dwordx4 v130, s[100:101]
	s_add_i32 m0, s9, 0x2000
	s_add_u32 s10, s84, 0x20080
	s_addc_u32 s11, s85, 0
	s_add_i32 s9, s12, s42
	global_load_lds_dwordx4 v134, s[100:101]
	s_mov_b32 m0, s9
	s_nop 0
	global_load_lds_dwordx4 v130, s[10:11]
	s_add_i32 m0, s9, 0x2000
	s_nop 0
	global_load_lds_dwordx4 v134, s[10:11]
	s_mov_b32 m0, s82
	s_add_u32 s100, s92, s60
	s_addc_u32 s101, s93, s61
	global_load_lds_dwordx4 v190, s[100:101]
	s_mov_b32 m0, s86
	s_nop 0
	global_load_lds_dwordx4 v132, s[100:101]
	s_waitcnt vmcnt(8)
	s_waitcnt lgkmcnt(0)
	s_barrier
	v_mfma_f32_16x16x32_bf16 v[62:65], v[152:155], v[194:197], v[62:65]
	v_mfma_f32_16x16x32_bf16 v[58:61], v[160:163], v[194:197], v[58:61]
	v_mfma_f32_16x16x32_bf16 v[54:57], v[152:155], v[210:213], v[54:57]
	v_mfma_f32_16x16x32_bf16 v[50:53], v[160:163], v[210:213], v[50:53]
	v_mfma_f32_16x16x32_bf16 v[46:49], v[152:155], v[218:221], v[46:49]
	v_mfma_f32_16x16x32_bf16 v[42:45], v[160:163], v[218:221], v[42:45]
	v_mfma_f32_16x16x32_bf16 v[38:41], v[152:155], v[240:243], v[38:41]
	v_mfma_f32_16x16x32_bf16 v[34:37], v[160:163], v[240:243], v[34:37]
	v_mfma_f32_16x16x32_bf16 v[62:65], v[156:159], v[206:209], v[62:65]
	v_mfma_f32_16x16x32_bf16 v[58:61], v[164:167], v[206:209], v[58:61]
	v_mfma_f32_16x16x32_bf16 v[54:57], v[156:159], v[214:217], v[54:57]
	v_mfma_f32_16x16x32_bf16 v[50:53], v[164:167], v[214:217], v[50:53]
	v_mfma_f32_16x16x32_bf16 v[46:49], v[156:159], v[236:239], v[46:49]
	v_mfma_f32_16x16x32_bf16 v[42:45], v[164:167], v[236:239], v[42:45]
	v_mfma_f32_16x16x32_bf16 v[38:41], v[156:159], v[244:247], v[38:41]
	v_mfma_f32_16x16x32_bf16 v[34:37], v[164:167], v[244:247], v[34:37]
	v_mfma_f32_16x16x32_bf16 v[30:33], v[168:171], v[194:197], v[30:33]
	v_mfma_f32_16x16x32_bf16 v[26:29], v[176:179], v[194:197], v[26:29]
	v_mfma_f32_16x16x32_bf16 v[22:25], v[168:171], v[210:213], v[22:25]
	v_mfma_f32_16x16x32_bf16 v[18:21], v[176:179], v[210:213], v[18:21]
	v_mfma_f32_16x16x32_bf16 v[14:17], v[168:171], v[218:221], v[14:17]
	v_mfma_f32_16x16x32_bf16 v[10:13], v[176:179], v[218:221], v[10:13]
	v_mfma_f32_16x16x32_bf16 v[6:9], v[168:171], v[240:243], v[6:9]
	v_mfma_f32_16x16x32_bf16 v[2:5], v[176:179], v[240:243], v[2:5]
	v_mfma_f32_16x16x32_bf16 v[30:33], v[172:175], v[206:209], v[30:33]
	v_mfma_f32_16x16x32_bf16 v[26:29], v[180:183], v[206:209], v[26:29]
	v_mfma_f32_16x16x32_bf16 v[22:25], v[172:175], v[214:217], v[22:25]
	v_mfma_f32_16x16x32_bf16 v[18:21], v[180:183], v[214:217], v[18:21]
	v_mfma_f32_16x16x32_bf16 v[14:17], v[172:175], v[236:239], v[14:17]
	v_mfma_f32_16x16x32_bf16 v[10:13], v[180:183], v[236:239], v[10:13]
	v_mfma_f32_16x16x32_bf16 v[6:9], v[172:175], v[244:247], v[6:9]
	v_mfma_f32_16x16x32_bf16 v[2:5], v[180:183], v[244:247], v[2:5]
	s_add_i32 s8, s8, 2
	s_add_u32 s80, s80, 0x100
	s_addc_u32 s81, s81, 0
	s_cmp_gt_u32 s8, 29
	s_barrier
	s_cbranch_scc0 .LBB0_1233
	s_and_b64 vcc, exec, s[62:63]
	s_cbranch_vccz .LBB0_1236
	s_barrier
